# combine phase: all 36 global loads per tile (gdn gated-rmsnorm + retention groupnorm inputs) hoisted ahead of compute into free VGPRs, counted vmcnt; on top of pipelined G1
# speedup vs baseline: 1.0213x; 1.0056x over previous
; #define LAS __attribute__((address_space(3)))
; __device__ NOINL void combine_phase(const LAS Params* lp, int l, LAS unsigned char* lds) {
;     ...
;     for (int tt = blockIdx.x; tt < ntt; tt += gridDim.x) {
;         const int row0 = tt * 64; const bool il = row0 < NLAT; const int L = il ? SEQ : CTXL;
;         const int b = il ? row0 / SEQ : (row0 - NLAT) / CTXL, t0 = il ? row0 % SEQ : (row0 - NLAT) % CTXL;
;         const bf16_t* hT = il ? p.hyO : p.hyOc;
;         __syncthreads();
;         {
;             const int ch = tid >> 1, hf = tid & 1;
;             const bf16_t* src = hT + ((size_t)ch * NB + b) * L + t0 + hf * 32;
; #pragma unroll
;             for (int q = 0; q < 4; ++q) {
;                 const u32x4 v = *(const u32x4*)(src + q * 8);
;                 const unsigned uu[4] = {v.x, v.y, v.z, v.w};
; #pragma unroll
;                 for (int e = 0; e < 4; ++e) { const int tk = hf * 32 + q * 8 + 2 * e; ts[tk * 264 + ch] = (bf16_t)(uu[e] & 0xFFFFu); ts[(tk + 1) * 264 + ch] = (bf16_t)(uu[e] >> 16); }
;             }
;         }
;         __syncthreads();
;         {
;             const int tk = tid >> 3, seg = (tid & 7) * 32;
; #pragma unroll
;             for (int q = 0; q < 4; ++q) *(u32x4*)(p.hbuf + (size_t)(row0 + tk) * DM + seg + q * 8) = *(const LAS u32x4*)(ts + tk * 264 + seg + q * 8);
;         }
; #pragma unroll
;         for (int i = 0; i < 8; ++i) {
;             const size_t row = (size_t)(row0 + 8 * w + i);
;             float of[8], ob[8], zz[8];
;             unpack8(*(const u32x4*)(p.hbuf + row * DM + 256 + lane * 8), of); unpack8(*(const u32x4*)(p.hyproj + row * 768 + lane * 8), ob); unpack8(*(const u32x4*)(p.proj + row * 3072 + 1536 + lane * 8), zz);
.LBB0_1396:
	s_ashr_i32 s41, s40, 31
	v_lshl_add_u64 v[16:17], v[2:3], 0, s[40:41]
	v_lshlrev_b64 v[16:17], s52, v[16:17]
	v_lshl_add_u64 v[16:17], v[16:17], 1, s[54:55]
	s_ashr_i32 s51, s50, 31
	v_lshl_add_u64 v[16:17], s[50:51], 1, v[16:17]
	v_lshl_add_u64 v[20:21], v[16:17], 0, v[0:1]
	s_barrier
	global_load_dwordx4 v[16:19], v[20:21], off
	s_add_i32 s29, s29, s88
	s_waitcnt vmcnt(0)
	ds_write_b16 v53, v16
	ds_write_b16_d16_hi v53, v16 offset:528
	ds_write_b16 v53, v17 offset:1056
	ds_write_b16_d16_hi v53, v17 offset:1584
	ds_write_b16 v53, v18 offset:2112
	ds_write_b16_d16_hi v53, v18 offset:2640
	ds_write_b16 v53, v19 offset:3168
	ds_write_b16_d16_hi v53, v19 offset:3696
	global_load_dwordx4 v[16:19], v[20:21], off offset:16
	s_waitcnt vmcnt(0)
	ds_write_b16 v53, v16 offset:4224
	ds_write_b16_d16_hi v53, v16 offset:4752
	ds_write_b16 v53, v17 offset:5280
	ds_write_b16_d16_hi v53, v17 offset:5808
	ds_write_b16 v53, v18 offset:6336
	ds_write_b16_d16_hi v53, v18 offset:6864
	ds_write_b16 v53, v19 offset:7392
	ds_write_b16_d16_hi v53, v19 offset:7920
	global_load_dwordx4 v[16:19], v[20:21], off offset:32
	s_waitcnt vmcnt(0)
	ds_write_b16 v53, v16 offset:8448
	ds_write_b16_d16_hi v53, v16 offset:8976
	ds_write_b16 v53, v17 offset:9504
	ds_write_b16_d16_hi v53, v17 offset:10032
	ds_write_b16 v53, v18 offset:10560
	ds_write_b16_d16_hi v53, v18 offset:11088
	ds_write_b16 v53, v19 offset:11616
	ds_write_b16_d16_hi v53, v19 offset:12144
	global_load_dwordx4 v[16:19], v[20:21], off offset:48
	s_waitcnt vmcnt(0)
	ds_write_b16 v53, v16 offset:12672
	ds_write_b16_d16_hi v53, v16 offset:13200
	ds_write_b16 v53, v17 offset:13728
	ds_write_b16_d16_hi v53, v17 offset:14256
	ds_write_b16 v53, v18 offset:14784
	ds_write_b16_d16_hi v53, v18 offset:15312
	ds_write_b16 v53, v19 offset:15840
	ds_write_b16_d16_hi v53, v19 offset:16368
	v_add_u32_e32 v16, s27, v46
	v_ashrrev_i32_e32 v17, 31, v16
	v_lshlrev_b64 v[16:17], 11, v[16:17]
	s_waitcnt lgkmcnt(0)
	s_barrier
	v_lshl_add_u64 v[56:57], v[24:25], 0, v[16:17]
	ds_read_b128 v[16:19], v47
	ds_read_b128 v[20:23], v47 offset:16
	ds_read_b128 v[38:41], v47 offset:32
	ds_read_b128 v[42:45], v47 offset:48
	s_waitcnt lgkmcnt(3)
	global_store_dwordx4 v[56:57], v[16:19], off
	s_waitcnt lgkmcnt(2)
	global_store_dwordx4 v[56:57], v[20:23], off offset:16
	s_waitcnt lgkmcnt(1)
	global_store_dwordx4 v[56:57], v[38:41], off offset:32
	s_waitcnt lgkmcnt(0)
	global_store_dwordx4 v[56:57], v[42:45], off offset:48
	v_add_u32_e32 v70, s27, v48
	v_ashrrev_i32_e32 v71, 31, v70
	v_lshlrev_b64 v[72:73], 11, v[70:71]
	v_lshl_add_u64 v[74:75], v[28:29], 0, v[72:73]
	v_mad_i64_i32 v[72:73], s[0:1], v70, s84, v[26:27]
	v_mad_i64_i32 v[76:77], s[0:1], v70, s81, v[30:31]
	global_load_dwordx4 v[78:81], v[74:75], off offset:512
	global_load_dwordx4 v[82:85], v[72:73], off
	global_load_dwordx4 v[86:89], v[76:77], off offset:3072
	v_add_u32_e32 v72, 1, v70
	v_ashrrev_i32_e32 v73, 31, v72
	v_mad_i64_i32 v[76:77], s[0:1], v72, s84, v[26:27]
	v_lshlrev_b64 v[90:91], 11, v[72:73]
	v_lshl_add_u64 v[92:93], v[28:29], 0, v[90:91]
	v_mad_i64_i32 v[90:91], s[0:1], v72, s81, v[30:31]
	global_load_dwordx4 v[94:97], v[92:93], off offset:512
	global_load_dwordx4 v[98:101], v[90:91], off offset:3072
	global_load_dwordx4 v[102:105], v[76:77], off
	v_add_u32_e32 v72, 2, v70
	v_ashrrev_i32_e32 v73, 31, v72
	v_mad_i64_i32 v[76:77], s[0:1], v72, s84, v[26:27]
	v_lshlrev_b64 v[90:91], 11, v[72:73]
	v_lshl_add_u64 v[106:107], v[28:29], 0, v[90:91]
	v_mad_i64_i32 v[90:91], s[0:1], v72, s81, v[30:31]
	global_load_dwordx4 v[108:111], v[106:107], off offset:512
	global_load_dwordx4 v[112:115], v[90:91], off offset:3072
	global_load_dwordx4 v[116:119], v[76:77], off
	v_add_u32_e32 v72, 3, v70
	v_ashrrev_i32_e32 v73, 31, v72
	v_mad_i64_i32 v[76:77], s[0:1], v72, s84, v[26:27]
	v_lshlrev_b64 v[90:91], 11, v[72:73]
	v_lshl_add_u64 v[120:121], v[28:29], 0, v[90:91]
	v_mad_i64_i32 v[90:91], s[0:1], v72, s81, v[30:31]
	global_load_dwordx4 v[122:125], v[120:121], off offset:512
	global_load_dwordx4 v[126:129], v[90:91], off offset:3072
	global_load_dwordx4 v[130:133], v[76:77], off
	v_add_u32_e32 v72, 4, v70
	v_ashrrev_i32_e32 v73, 31, v72
	v_mad_i64_i32 v[76:77], s[0:1], v72, s84, v[26:27]
	v_lshlrev_b64 v[90:91], 11, v[72:73]
	v_lshl_add_u64 v[134:135], v[28:29], 0, v[90:91]
	v_mad_i64_i32 v[90:91], s[0:1], v72, s81, v[30:31]
	global_load_dwordx4 v[136:139], v[134:135], off offset:512
	global_load_dwordx4 v[140:143], v[90:91], off offset:3072
	global_load_dwordx4 v[144:147], v[76:77], off
	v_add_u32_e32 v72, 5, v70
	v_ashrrev_i32_e32 v73, 31, v72
	v_mad_i64_i32 v[76:77], s[0:1], v72, s84, v[26:27]
	v_lshlrev_b64 v[90:91], 11, v[72:73]
	v_lshl_add_u64 v[148:149], v[28:29], 0, v[90:91]
	v_mad_i64_i32 v[90:91], s[0:1], v72, s81, v[30:31]
	global_load_dwordx4 v[150:153], v[148:149], off offset:512
	global_load_dwordx4 v[154:157], v[90:91], off offset:3072
	global_load_dwordx4 v[158:161], v[76:77], off
	v_add_u32_e32 v72, 6, v70
	v_ashrrev_i32_e32 v73, 31, v72
	v_mad_i64_i32 v[76:77], s[0:1], v72, s84, v[26:27]
	v_lshlrev_b64 v[90:91], 11, v[72:73]
	v_lshl_add_u64 v[162:163], v[28:29], 0, v[90:91]
	v_mad_i64_i32 v[90:91], s[0:1], v72, s81, v[30:31]
	global_load_dwordx4 v[164:167], v[162:163], off offset:512
	global_load_dwordx4 v[168:171], v[90:91], off offset:3072
	global_load_dwordx4 v[172:175], v[76:77], off
	v_add_u32_e32 v72, 7, v70
	v_ashrrev_i32_e32 v73, 31, v72
	v_lshlrev_b64 v[70:71], 11, v[72:73]
	v_lshl_add_u64 v[76:77], v[28:29], 0, v[70:71]
	v_mad_i64_i32 v[70:71], s[0:1], v72, s84, v[26:27]
	v_mad_i64_i32 v[90:91], s[0:1], v72, s81, v[30:31]
	global_load_dwordx4 v[176:179], v[76:77], off offset:512
	global_load_dwordx4 v[180:183], v[90:91], off offset:3072
	global_load_dwordx4 v[186:189], v[70:71], off
	s_waitcnt vmcnt(23)
; __device__ __forceinline__ unsigned pk2(float lo, float hi) { const f32v2_t f = {lo, hi}; const bf16v2_t b = __builtin_convertvector(f, bf16v2_t); return __builtin_bit_cast(unsigned, b); }
; __device__ __forceinline__ float siluf(float v) { return v * __builtin_amdgcn_rcpf(1.f + __expf(-v)); }
; __device__ NOINL void combine_phase(const LAS Params* lp, int l, LAS unsigned char* lds) {
;     ...
;         for (int i = 0; i < 8; ++i) {
;             const size_t row = (size_t)(row0 + 8 * w + i);
;             float of[8], ob[8], zz[8];
;             unpack8(*(const u32x4*)(p.hbuf + row * DM + 256 + lane * 8), of); unpack8(*(const u32x4*)(p.hyproj + row * 768 + lane * 8), ob); unpack8(*(const u32x4*)(p.proj + row * 3072 + 1536 + lane * 8), zz);
;             float ss = 0.f;
; #pragma unroll
;             for (int e = 0; e < 8; ++e) { of[e] += ob[e]; ss += of[e] * of[e]; }
;             ss += __shfl_xor(ss, 1); ss += __shfl_xor(ss, 2); ss += __shfl_xor(ss, 4); ss += __shfl_xor(ss, 8);
;             const float inv = rsqrtf(ss * (1.f / 128.f) + 1e-6f);
;             float o[8];
; #pragma unroll
;             for (int e = 0; e < 8; ++e) o[e] = of[e] * inv * ng8[e] * siluf(zz[e]);
;             u32x4 pk; pk.x = pk2(o[0], o[1]); pk.y = pk2(o[2], o[3]); pk.z = pk2(o[4], o[5]); pk.w = pk2(o[6], o[7]);
;             *(u32x4*)(p.hbuf + row * DM + 256 + lane * 8) = pk;
	v_lshlrev_b32_e32 v56, 16, v81
	v_and_b32_e32 v57, 0xffff0000, v81
	v_lshlrev_b32_e32 v62, 16, v80
	v_and_b32_e32 v63, 0xffff0000, v80
	s_waitcnt vmcnt(22)
	v_lshlrev_b32_e32 v18, 16, v84
	v_and_b32_e32 v19, 0xffff0000, v84
	s_waitcnt vmcnt(21)
	v_lshlrev_b32_e32 v40, 16, v88
	v_mul_f32_e32 v21, 0xbfb8aa3b, v40
	v_exp_f32_e32 v21, v21
	v_lshlrev_b32_e32 v58, 16, v85
	v_and_b32_e32 v59, 0xffff0000, v85
	v_and_b32_e32 v41, 0xffff0000, v88
	v_add_f32_e32 v21, 1.0, v21
	v_pk_add_f32 v[18:19], v[62:63], v[18:19]
	v_rcp_f32_e32 v62, v21
	v_mul_f32_e32 v21, 0xbfb8aa3b, v41
	v_exp_f32_e32 v21, v21
	v_lshlrev_b32_e32 v66, 16, v87
	v_and_b32_e32 v67, 0xffff0000, v87
	v_lshlrev_b32_e32 v64, 16, v83
	v_add_f32_e32 v21, 1.0, v21
	v_rcp_f32_e32 v63, v21
	v_and_b32_e32 v65, 0xffff0000, v83
	v_and_b32_e32 v39, 0xffff0000, v86
	v_lshlrev_b32_e32 v60, 16, v89
	v_pk_mul_f32 v[40:41], v[62:63], v[40:41]
	v_lshlrev_b32_e32 v62, 16, v79
	v_and_b32_e32 v63, 0xffff0000, v79
	v_mul_f32_e32 v17, 0xbfb8aa3b, v66
	v_exp_f32_e32 v17, v17
	v_pk_add_f32 v[62:63], v[62:63], v[64:65]
	v_and_b32_e32 v61, 0xffff0000, v89
	v_pk_mul_f32 v[64:65], v[62:63], v[62:63]
	v_add_f32_e32 v17, 1.0, v17
	v_rcp_f32_e32 v68, v17
	v_mul_f32_e32 v17, 0xbfb8aa3b, v67
	v_exp_f32_e32 v17, v17
	v_pk_mul_f32 v[44:45], v[18:19], v[18:19]
	v_pk_add_f32 v[56:57], v[56:57], v[58:59]
	v_add_f32_e32 v17, 1.0, v17
	v_rcp_f32_e32 v69, v17
	v_and_b32_e32 v17, 0xffff0000, v82
	v_pk_mul_f32 v[58:59], v[56:57], v[56:57]
	v_pk_mul_f32 v[66:67], v[68:69], v[66:67]
	v_lshlrev_b32_e32 v68, 16, v78
	v_and_b32_e32 v69, 0xffff0000, v78
	v_lshlrev_b32_e32 v16, 16, v82
	v_lshlrev_b32_e32 v38, 16, v86
	v_mul_f32_e32 v21, 0xbfb8aa3b, v38
	v_exp_f32_e32 v21, v21
	v_pk_add_f32 v[16:17], v[68:69], v[16:17]
	v_add_f32_e32 v21, 1.0, v21
	v_rcp_f32_e32 v68, v21
	v_mul_f32_e32 v21, 0xbfb8aa3b, v39
	v_exp_f32_e32 v21, v21
	v_pk_mul_f32 v[42:43], v[16:17], v[16:17]
	v_add_f32_e32 v21, 1.0, v21
	v_rcp_f32_e32 v69, v21
	v_add_f32_e32 v21, v42, v43
	v_add_f32_e32 v21, v64, v21
	v_add_f32_e32 v21, v65, v21
	v_add_f32_e32 v21, v44, v21
	v_add_f32_e32 v21, v45, v21
	v_add_f32_e32 v21, v58, v21
	v_add_f32_e32 v21, v59, v21
	ds_bpermute_b32 v37, v49, v21
	v_pk_mul_f32 v[38:39], v[68:69], v[38:39]
	s_waitcnt lgkmcnt(0)
	v_add_f32_e32 v21, v21, v37
	ds_bpermute_b32 v37, v50, v21
	s_waitcnt lgkmcnt(0)
	v_add_f32_e32 v21, v21, v37
	ds_bpermute_b32 v37, v51, v21
	s_waitcnt lgkmcnt(0)
	v_add_f32_e32 v21, v21, v37
	ds_bpermute_b32 v37, v52, v21
	s_waitcnt lgkmcnt(0)
	v_add_f32_e32 v21, v21, v37
	v_fmamk_f32 v21, v21, 0x3c000000, v211
	v_cmp_gt_f32_e32 vcc, s79, v21
	v_mul_f32_e32 v37, 0x4b800000, v21
	s_nop 0
	v_cndmask_b32_e32 v21, v21, v37, vcc
	v_rsq_f32_e32 v21, v21
	s_nop 0
	v_mul_f32_e32 v37, 0x45800000, v21
	v_cndmask_b32_e32 v42, v21, v37, vcc
	v_mul_f32_e32 v21, 0xbfb8aa3b, v60
	v_exp_f32_e32 v21, v21
	v_pk_mul_f32 v[18:19], v[18:19], v[42:43] op_sel_hi:[1,0]
	v_pk_mul_f32 v[16:17], v[16:17], v[42:43] op_sel_hi:[1,0]
	v_pk_mul_f32 v[18:19], v[8:9], v[18:19]
	v_add_f32_e32 v21, 1.0, v21
	v_pk_mul_f32 v[18:19], v[40:41], v[18:19]
	v_rcp_f32_e32 v40, v21
	v_mul_f32_e32 v21, 0xbfb8aa3b, v61
	v_exp_f32_e32 v21, v21
	v_pk_mul_f32 v[16:17], v[12:13], v[16:17]
	v_cvt_pk_bf16_f32 v18, v18, v19
	v_pk_mul_f32 v[16:17], v[38:39], v[16:17]
	v_add_f32_e32 v21, 1.0, v21
	v_rcp_f32_e32 v41, v21
	v_pk_mul_f32 v[38:39], v[62:63], v[42:43] op_sel_hi:[1,0]
	v_pk_mul_f32 v[42:43], v[56:57], v[42:43] op_sel_hi:[1,0]
	v_pk_mul_f32 v[38:39], v[14:15], v[38:39]
	v_pk_mul_f32 v[42:43], v[10:11], v[42:43]
	v_pk_mul_f32 v[38:39], v[66:67], v[38:39]
	v_pk_mul_f32 v[40:41], v[40:41], v[60:61]
	v_cvt_pk_bf16_f32 v16, v16, v17
	v_pk_mul_f32 v[40:41], v[40:41], v[42:43]
	v_cvt_pk_bf16_f32 v17, v38, v39
	v_cvt_pk_bf16_f32 v19, v40, v41
	global_store_dwordx4 v[74:75], v[16:19], off offset:512
	s_nop 0
	s_waitcnt vmcnt(21)
	v_lshlrev_b32_e32 v38, 16, v97
	v_and_b32_e32 v39, 0xffff0000, v97
	v_lshlrev_b32_e32 v62, 16, v96
	v_and_b32_e32 v63, 0xffff0000, v96
	s_waitcnt vmcnt(20)
	v_lshlrev_b32_e32 v66, 16, v99
	v_and_b32_e32 v67, 0xffff0000, v99
	v_lshlrev_b32_e32 v60, 16, v101
	v_and_b32_e32 v61, 0xffff0000, v101
	s_waitcnt vmcnt(19)
	v_lshlrev_b32_e32 v18, 16, v104
	v_and_b32_e32 v19, 0xffff0000, v104
	v_lshlrev_b32_e32 v42, 16, v100
	v_mul_f32_e32 v21, 0xbfb8aa3b, v42
	v_exp_f32_e32 v21, v21
	v_lshlrev_b32_e32 v44, 16, v105
	v_and_b32_e32 v45, 0xffff0000, v105
	v_and_b32_e32 v43, 0xffff0000, v100
	v_add_f32_e32 v21, 1.0, v21
	v_pk_add_f32 v[18:19], v[62:63], v[18:19]
	v_rcp_f32_e32 v62, v21
	v_mul_f32_e32 v21, 0xbfb8aa3b, v43
	v_exp_f32_e32 v21, v21
	v_lshlrev_b32_e32 v64, 16, v103
	v_and_b32_e32 v65, 0xffff0000, v103
	v_and_b32_e32 v41, 0xffff0000, v98
	v_add_f32_e32 v21, 1.0, v21
	v_rcp_f32_e32 v63, v21
	v_pk_mul_f32 v[58:59], v[18:19], v[18:19]
	v_pk_add_f32 v[38:39], v[38:39], v[44:45]
	v_pk_mul_f32 v[42:43], v[62:63], v[42:43]
	v_lshlrev_b32_e32 v62, 16, v95
	v_and_b32_e32 v63, 0xffff0000, v95
	v_mul_f32_e32 v17, 0xbfb8aa3b, v66
	v_exp_f32_e32 v17, v17
	v_pk_add_f32 v[62:63], v[62:63], v[64:65]
	v_pk_mul_f32 v[44:45], v[38:39], v[38:39]
	v_pk_mul_f32 v[64:65], v[62:63], v[62:63]
	v_add_f32_e32 v17, 1.0, v17
	v_rcp_f32_e32 v68, v17
	v_mul_f32_e32 v17, 0xbfb8aa3b, v67
	v_exp_f32_e32 v17, v17
	s_nop 0
	v_add_f32_e32 v17, 1.0, v17
	v_rcp_f32_e32 v69, v17
	v_and_b32_e32 v17, 0xffff0000, v102
	v_pk_mul_f32 v[66:67], v[68:69], v[66:67]
	v_lshlrev_b32_e32 v68, 16, v94
	v_and_b32_e32 v69, 0xffff0000, v94
	v_lshlrev_b32_e32 v16, 16, v102
	v_lshlrev_b32_e32 v40, 16, v98
	v_mul_f32_e32 v21, 0xbfb8aa3b, v40
	v_exp_f32_e32 v21, v21
	v_pk_add_f32 v[16:17], v[68:69], v[16:17]
	v_add_f32_e32 v21, 1.0, v21
	v_rcp_f32_e32 v68, v21
	v_mul_f32_e32 v21, 0xbfb8aa3b, v41
	v_exp_f32_e32 v21, v21
	v_pk_mul_f32 v[56:57], v[16:17], v[16:17]
	v_add_f32_e32 v21, 1.0, v21
	v_rcp_f32_e32 v69, v21
	v_add_f32_e32 v21, v56, v57
	v_add_f32_e32 v21, v64, v21
	v_add_f32_e32 v21, v65, v21
	v_add_f32_e32 v21, v58, v21
	v_add_f32_e32 v21, v59, v21
	v_add_f32_e32 v21, v44, v21
	v_add_f32_e32 v21, v45, v21
	ds_bpermute_b32 v37, v49, v21
	v_pk_mul_f32 v[40:41], v[68:69], v[40:41]
	s_waitcnt lgkmcnt(0)
; __device__ __forceinline__ unsigned pk2(float lo, float hi) { const f32v2_t f = {lo, hi}; const bf16v2_t b = __builtin_convertvector(f, bf16v2_t); return __builtin_bit_cast(unsigned, b); }
; __device__ __forceinline__ float siluf(float v) { return v * __builtin_amdgcn_rcpf(1.f + __expf(-v)); }
; __device__ NOINL void combine_phase(const LAS Params* lp, int l, LAS unsigned char* lds) {
;     ...
;         for (int i = 0; i < 8; ++i) {
;             const size_t row = (size_t)(row0 + 8 * w + i);
;             float of[8], ob[8], zz[8];
;             unpack8(*(const u32x4*)(p.hbuf + row * DM + 256 + lane * 8), of); unpack8(*(const u32x4*)(p.hyproj + row * 768 + lane * 8), ob); unpack8(*(const u32x4*)(p.proj + row * 3072 + 1536 + lane * 8), zz);
;             float ss = 0.f;
; #pragma unroll
;             for (int e = 0; e < 8; ++e) { of[e] += ob[e]; ss += of[e] * of[e]; }
;             ss += __shfl_xor(ss, 1); ss += __shfl_xor(ss, 2); ss += __shfl_xor(ss, 4); ss += __shfl_xor(ss, 8);
;             const float inv = rsqrtf(ss * (1.f / 128.f) + 1e-6f);
;             float o[8];
; #pragma unroll
;             for (int e = 0; e < 8; ++e) o[e] = of[e] * inv * ng8[e] * siluf(zz[e]);
;             u32x4 pk; pk.x = pk2(o[0], o[1]); pk.y = pk2(o[2], o[3]); pk.z = pk2(o[4], o[5]); pk.w = pk2(o[6], o[7]);
;             *(u32x4*)(p.hbuf + row * DM + 256 + lane * 8) = pk;
	v_add_f32_e32 v21, v21, v37
	ds_bpermute_b32 v37, v50, v21
	s_waitcnt lgkmcnt(0)
	v_add_f32_e32 v21, v21, v37
	ds_bpermute_b32 v37, v51, v21
	s_waitcnt lgkmcnt(0)
	v_add_f32_e32 v21, v21, v37
	ds_bpermute_b32 v37, v52, v21
	s_waitcnt lgkmcnt(0)
	v_add_f32_e32 v21, v21, v37
	v_fmamk_f32 v21, v21, 0x3c000000, v211
	v_cmp_gt_f32_e32 vcc, s79, v21
	v_mul_f32_e32 v37, 0x4b800000, v21
	s_nop 0
	v_cndmask_b32_e32 v21, v21, v37, vcc
	v_rsq_f32_e32 v21, v21
	s_nop 0
	v_mul_f32_e32 v37, 0x45800000, v21
	v_cndmask_b32_e32 v44, v21, v37, vcc
	v_mul_f32_e32 v21, 0xbfb8aa3b, v60
	v_exp_f32_e32 v21, v21
	v_pk_mul_f32 v[18:19], v[18:19], v[44:45] op_sel_hi:[1,0]
	v_pk_mul_f32 v[16:17], v[16:17], v[44:45] op_sel_hi:[1,0]
	v_pk_mul_f32 v[18:19], v[8:9], v[18:19]
	v_add_f32_e32 v21, 1.0, v21
	v_pk_mul_f32 v[18:19], v[42:43], v[18:19]
	v_rcp_f32_e32 v42, v21
	v_mul_f32_e32 v21, 0xbfb8aa3b, v61
	v_exp_f32_e32 v21, v21
	v_pk_mul_f32 v[16:17], v[12:13], v[16:17]
	v_pk_mul_f32 v[38:39], v[38:39], v[44:45] op_sel_hi:[1,0]
	v_pk_mul_f32 v[16:17], v[40:41], v[16:17]
	v_add_f32_e32 v21, 1.0, v21
	v_rcp_f32_e32 v43, v21
	v_pk_mul_f32 v[40:41], v[62:63], v[44:45] op_sel_hi:[1,0]
	v_pk_mul_f32 v[38:39], v[10:11], v[38:39]
	v_pk_mul_f32 v[40:41], v[14:15], v[40:41]
	v_pk_mul_f32 v[42:43], v[42:43], v[60:61]
	v_pk_mul_f32 v[40:41], v[66:67], v[40:41]
	v_pk_mul_f32 v[38:39], v[42:43], v[38:39]
	v_cvt_pk_bf16_f32 v18, v18, v19
	v_cvt_pk_bf16_f32 v19, v38, v39
	v_cvt_pk_bf16_f32 v16, v16, v17
	v_cvt_pk_bf16_f32 v17, v40, v41
	global_store_dwordx4 v[92:93], v[16:19], off offset:512
	s_nop 0
	s_waitcnt vmcnt(19)
	v_lshlrev_b32_e32 v38, 16, v111
	v_and_b32_e32 v39, 0xffff0000, v111
	v_lshlrev_b32_e32 v62, 16, v110
	v_and_b32_e32 v63, 0xffff0000, v110
	s_waitcnt vmcnt(18)
	v_lshlrev_b32_e32 v66, 16, v113
	v_and_b32_e32 v67, 0xffff0000, v113
	v_lshlrev_b32_e32 v60, 16, v115
	v_and_b32_e32 v61, 0xffff0000, v115
	s_waitcnt vmcnt(17)
	v_lshlrev_b32_e32 v18, 16, v118
	v_and_b32_e32 v19, 0xffff0000, v118
	v_lshlrev_b32_e32 v42, 16, v114
	v_mul_f32_e32 v21, 0xbfb8aa3b, v42
	v_exp_f32_e32 v21, v21
	v_lshlrev_b32_e32 v44, 16, v119
	v_and_b32_e32 v45, 0xffff0000, v119
	v_and_b32_e32 v43, 0xffff0000, v114
	v_add_f32_e32 v21, 1.0, v21
	v_pk_add_f32 v[18:19], v[62:63], v[18:19]
	v_rcp_f32_e32 v62, v21
	v_mul_f32_e32 v21, 0xbfb8aa3b, v43
	v_exp_f32_e32 v21, v21
	v_lshlrev_b32_e32 v64, 16, v117
	v_and_b32_e32 v65, 0xffff0000, v117
	v_and_b32_e32 v41, 0xffff0000, v112
	v_add_f32_e32 v21, 1.0, v21
	v_rcp_f32_e32 v63, v21
	v_pk_mul_f32 v[58:59], v[18:19], v[18:19]
	v_pk_add_f32 v[38:39], v[38:39], v[44:45]
	v_pk_mul_f32 v[42:43], v[62:63], v[42:43]
	v_lshlrev_b32_e32 v62, 16, v109
	v_and_b32_e32 v63, 0xffff0000, v109
	v_mul_f32_e32 v17, 0xbfb8aa3b, v66
	v_exp_f32_e32 v17, v17
	v_pk_add_f32 v[62:63], v[62:63], v[64:65]
	v_pk_mul_f32 v[44:45], v[38:39], v[38:39]
	v_pk_mul_f32 v[64:65], v[62:63], v[62:63]
	v_add_f32_e32 v17, 1.0, v17
	v_rcp_f32_e32 v68, v17
	v_mul_f32_e32 v17, 0xbfb8aa3b, v67
	v_exp_f32_e32 v17, v17
	s_nop 0
	v_add_f32_e32 v17, 1.0, v17
	v_rcp_f32_e32 v69, v17
	v_and_b32_e32 v17, 0xffff0000, v116
	v_pk_mul_f32 v[66:67], v[68:69], v[66:67]
	v_lshlrev_b32_e32 v68, 16, v108
	v_and_b32_e32 v69, 0xffff0000, v108
	v_lshlrev_b32_e32 v16, 16, v116
	v_lshlrev_b32_e32 v40, 16, v112
	v_mul_f32_e32 v21, 0xbfb8aa3b, v40
	v_exp_f32_e32 v21, v21
	v_pk_add_f32 v[16:17], v[68:69], v[16:17]
	v_add_f32_e32 v21, 1.0, v21
	v_rcp_f32_e32 v68, v21
	v_mul_f32_e32 v21, 0xbfb8aa3b, v41
	v_exp_f32_e32 v21, v21
	v_pk_mul_f32 v[56:57], v[16:17], v[16:17]
	v_add_f32_e32 v21, 1.0, v21
	v_rcp_f32_e32 v69, v21
	v_add_f32_e32 v21, v56, v57
	v_add_f32_e32 v21, v64, v21
	v_add_f32_e32 v21, v65, v21
	v_add_f32_e32 v21, v58, v21
	v_add_f32_e32 v21, v59, v21
	v_add_f32_e32 v21, v44, v21
	v_add_f32_e32 v21, v45, v21
	ds_bpermute_b32 v37, v49, v21
	v_pk_mul_f32 v[40:41], v[68:69], v[40:41]
	s_waitcnt lgkmcnt(0)
	v_add_f32_e32 v21, v21, v37
	ds_bpermute_b32 v37, v50, v21
	s_waitcnt lgkmcnt(0)
	v_add_f32_e32 v21, v21, v37
	ds_bpermute_b32 v37, v51, v21
	s_waitcnt lgkmcnt(0)
	v_add_f32_e32 v21, v21, v37
	ds_bpermute_b32 v37, v52, v21
	s_waitcnt lgkmcnt(0)
	v_add_f32_e32 v21, v21, v37
	v_fmamk_f32 v21, v21, 0x3c000000, v211
	v_cmp_gt_f32_e32 vcc, s79, v21
	v_mul_f32_e32 v37, 0x4b800000, v21
	s_nop 0
	v_cndmask_b32_e32 v21, v21, v37, vcc
	v_rsq_f32_e32 v21, v21
	s_nop 0
	v_mul_f32_e32 v37, 0x45800000, v21
	v_cndmask_b32_e32 v44, v21, v37, vcc
	v_mul_f32_e32 v21, 0xbfb8aa3b, v60
	v_exp_f32_e32 v21, v21
	v_pk_mul_f32 v[18:19], v[18:19], v[44:45] op_sel_hi:[1,0]
	v_pk_mul_f32 v[16:17], v[16:17], v[44:45] op_sel_hi:[1,0]
	v_pk_mul_f32 v[18:19], v[8:9], v[18:19]
	v_add_f32_e32 v21, 1.0, v21
	v_pk_mul_f32 v[18:19], v[42:43], v[18:19]
	v_rcp_f32_e32 v42, v21
	v_mul_f32_e32 v21, 0xbfb8aa3b, v61
	v_exp_f32_e32 v21, v21
	v_pk_mul_f32 v[16:17], v[12:13], v[16:17]
	v_pk_mul_f32 v[38:39], v[38:39], v[44:45] op_sel_hi:[1,0]
	v_pk_mul_f32 v[16:17], v[40:41], v[16:17]
	v_add_f32_e32 v21, 1.0, v21
	v_rcp_f32_e32 v43, v21
	v_pk_mul_f32 v[40:41], v[62:63], v[44:45] op_sel_hi:[1,0]
	v_pk_mul_f32 v[38:39], v[10:11], v[38:39]
	v_pk_mul_f32 v[40:41], v[14:15], v[40:41]
	v_pk_mul_f32 v[42:43], v[42:43], v[60:61]
	v_pk_mul_f32 v[40:41], v[66:67], v[40:41]
	v_pk_mul_f32 v[38:39], v[42:43], v[38:39]
	v_cvt_pk_bf16_f32 v18, v18, v19
	v_cvt_pk_bf16_f32 v19, v38, v39
	v_cvt_pk_bf16_f32 v16, v16, v17
	v_cvt_pk_bf16_f32 v17, v40, v41
	global_store_dwordx4 v[106:107], v[16:19], off offset:512
	s_nop 0
	s_waitcnt vmcnt(17)
	v_lshlrev_b32_e32 v38, 16, v125
	v_and_b32_e32 v39, 0xffff0000, v125
	v_lshlrev_b32_e32 v62, 16, v124
	v_and_b32_e32 v63, 0xffff0000, v124
	s_waitcnt vmcnt(16)
; __device__ __forceinline__ unsigned pk2(float lo, float hi) { const f32v2_t f = {lo, hi}; const bf16v2_t b = __builtin_convertvector(f, bf16v2_t); return __builtin_bit_cast(unsigned, b); }
; __device__ __forceinline__ float siluf(float v) { return v * __builtin_amdgcn_rcpf(1.f + __expf(-v)); }
; __device__ NOINL void combine_phase(const LAS Params* lp, int l, LAS unsigned char* lds) {
;     ...
;         for (int i = 0; i < 8; ++i) {
;             const size_t row = (size_t)(row0 + 8 * w + i);
;             float of[8], ob[8], zz[8];
;             unpack8(*(const u32x4*)(p.hbuf + row * DM + 256 + lane * 8), of); unpack8(*(const u32x4*)(p.hyproj + row * 768 + lane * 8), ob); unpack8(*(const u32x4*)(p.proj + row * 3072 + 1536 + lane * 8), zz);
;             float ss = 0.f;
; #pragma unroll
;             for (int e = 0; e < 8; ++e) { of[e] += ob[e]; ss += of[e] * of[e]; }
;             ss += __shfl_xor(ss, 1); ss += __shfl_xor(ss, 2); ss += __shfl_xor(ss, 4); ss += __shfl_xor(ss, 8);
;             const float inv = rsqrtf(ss * (1.f / 128.f) + 1e-6f);
;             float o[8];
; #pragma unroll
;             for (int e = 0; e < 8; ++e) o[e] = of[e] * inv * ng8[e] * siluf(zz[e]);
;             u32x4 pk; pk.x = pk2(o[0], o[1]); pk.y = pk2(o[2], o[3]); pk.z = pk2(o[4], o[5]); pk.w = pk2(o[6], o[7]);
;             *(u32x4*)(p.hbuf + row * DM + 256 + lane * 8) = pk;
;         }
; #pragma unroll
;         for (int i = 0; i < 4; ++i) {
;             const size_t row = (size_t)(row0 + 8 * w + 2 * i + (lane >> 5)); const int l32 = lane & 31;
;             float of[8], ob[8], gg[8];
;             unpack8(*(const u32x4*)(p.hbuf + row * DM + 768 + l32 * 8), of); unpack8(*(const u32x4*)(p.hyproj + row * 768 + 512 + l32 * 8), ob); unpack8(*(const u32x4*)(p.proj + row * 3072 + 2816 + l32 * 8), gg);
	v_lshlrev_b32_e32 v66, 16, v127
	v_and_b32_e32 v67, 0xffff0000, v127
	v_lshlrev_b32_e32 v60, 16, v129
	v_and_b32_e32 v61, 0xffff0000, v129
	s_waitcnt vmcnt(15)
	v_lshlrev_b32_e32 v18, 16, v132
	v_and_b32_e32 v19, 0xffff0000, v132
	v_lshlrev_b32_e32 v42, 16, v128
	v_mul_f32_e32 v21, 0xbfb8aa3b, v42
	v_exp_f32_e32 v21, v21
	v_lshlrev_b32_e32 v44, 16, v133
	v_and_b32_e32 v45, 0xffff0000, v133
	v_and_b32_e32 v43, 0xffff0000, v128
	v_add_f32_e32 v21, 1.0, v21
	v_pk_add_f32 v[18:19], v[62:63], v[18:19]
	v_rcp_f32_e32 v62, v21
	v_mul_f32_e32 v21, 0xbfb8aa3b, v43
	v_exp_f32_e32 v21, v21
	v_lshlrev_b32_e32 v64, 16, v131
	v_and_b32_e32 v65, 0xffff0000, v131
	v_and_b32_e32 v41, 0xffff0000, v126
	v_add_f32_e32 v21, 1.0, v21
	v_rcp_f32_e32 v63, v21
	v_pk_mul_f32 v[58:59], v[18:19], v[18:19]
	v_pk_add_f32 v[38:39], v[38:39], v[44:45]
	v_pk_mul_f32 v[42:43], v[62:63], v[42:43]
	v_lshlrev_b32_e32 v62, 16, v123
	v_and_b32_e32 v63, 0xffff0000, v123
	v_mul_f32_e32 v17, 0xbfb8aa3b, v66
	v_exp_f32_e32 v17, v17
	v_pk_add_f32 v[62:63], v[62:63], v[64:65]
	v_pk_mul_f32 v[44:45], v[38:39], v[38:39]
	v_pk_mul_f32 v[64:65], v[62:63], v[62:63]
	v_add_f32_e32 v17, 1.0, v17
	v_rcp_f32_e32 v68, v17
	v_mul_f32_e32 v17, 0xbfb8aa3b, v67
	v_exp_f32_e32 v17, v17
	s_nop 0
	v_add_f32_e32 v17, 1.0, v17
	v_rcp_f32_e32 v69, v17
	v_and_b32_e32 v17, 0xffff0000, v130
	v_pk_mul_f32 v[66:67], v[68:69], v[66:67]
	v_lshlrev_b32_e32 v68, 16, v122
	v_and_b32_e32 v69, 0xffff0000, v122
	v_lshlrev_b32_e32 v16, 16, v130
	v_lshlrev_b32_e32 v40, 16, v126
	v_mul_f32_e32 v21, 0xbfb8aa3b, v40
	v_exp_f32_e32 v21, v21
	v_pk_add_f32 v[16:17], v[68:69], v[16:17]
	v_add_f32_e32 v21, 1.0, v21
	v_rcp_f32_e32 v68, v21
	v_mul_f32_e32 v21, 0xbfb8aa3b, v41
	v_exp_f32_e32 v21, v21
	v_pk_mul_f32 v[56:57], v[16:17], v[16:17]
	v_add_f32_e32 v21, 1.0, v21
	v_rcp_f32_e32 v69, v21
	v_add_f32_e32 v21, v56, v57
	v_add_f32_e32 v21, v64, v21
	v_add_f32_e32 v21, v65, v21
	v_add_f32_e32 v21, v58, v21
	v_add_f32_e32 v21, v59, v21
	v_add_f32_e32 v21, v44, v21
	v_add_f32_e32 v21, v45, v21
	ds_bpermute_b32 v37, v49, v21
	v_pk_mul_f32 v[40:41], v[68:69], v[40:41]
	s_waitcnt lgkmcnt(0)
	v_add_f32_e32 v21, v21, v37
	ds_bpermute_b32 v37, v50, v21
	s_waitcnt lgkmcnt(0)
	v_add_f32_e32 v21, v21, v37
	ds_bpermute_b32 v37, v51, v21
	s_waitcnt lgkmcnt(0)
	v_add_f32_e32 v21, v21, v37
	ds_bpermute_b32 v37, v52, v21
	s_waitcnt lgkmcnt(0)
	v_add_f32_e32 v21, v21, v37
	v_fmamk_f32 v21, v21, 0x3c000000, v211
	v_cmp_gt_f32_e32 vcc, s79, v21
	v_mul_f32_e32 v37, 0x4b800000, v21
	s_nop 0
	v_cndmask_b32_e32 v21, v21, v37, vcc
	v_rsq_f32_e32 v21, v21
	s_nop 0
	v_mul_f32_e32 v37, 0x45800000, v21
	v_cndmask_b32_e32 v44, v21, v37, vcc
	v_mul_f32_e32 v21, 0xbfb8aa3b, v60
	v_exp_f32_e32 v21, v21
	v_pk_mul_f32 v[18:19], v[18:19], v[44:45] op_sel_hi:[1,0]
	v_pk_mul_f32 v[16:17], v[16:17], v[44:45] op_sel_hi:[1,0]
	v_pk_mul_f32 v[18:19], v[8:9], v[18:19]
	v_add_f32_e32 v21, 1.0, v21
	v_pk_mul_f32 v[18:19], v[42:43], v[18:19]
	v_rcp_f32_e32 v42, v21
	v_mul_f32_e32 v21, 0xbfb8aa3b, v61
	v_exp_f32_e32 v21, v21
	v_pk_mul_f32 v[16:17], v[12:13], v[16:17]
	v_pk_mul_f32 v[38:39], v[38:39], v[44:45] op_sel_hi:[1,0]
	v_pk_mul_f32 v[16:17], v[40:41], v[16:17]
	v_add_f32_e32 v21, 1.0, v21
	v_rcp_f32_e32 v43, v21
	v_pk_mul_f32 v[40:41], v[62:63], v[44:45] op_sel_hi:[1,0]
	v_pk_mul_f32 v[38:39], v[10:11], v[38:39]
	v_pk_mul_f32 v[40:41], v[14:15], v[40:41]
	v_pk_mul_f32 v[42:43], v[42:43], v[60:61]
	v_pk_mul_f32 v[40:41], v[66:67], v[40:41]
	v_pk_mul_f32 v[38:39], v[42:43], v[38:39]
	v_cvt_pk_bf16_f32 v18, v18, v19
	v_cvt_pk_bf16_f32 v19, v38, v39
	v_cvt_pk_bf16_f32 v16, v16, v17
	v_cvt_pk_bf16_f32 v17, v40, v41
	global_store_dwordx4 v[120:121], v[16:19], off offset:512
	v_add_u32_e32 v70, s27, v54
	v_mov_b64_e32 v[72:73], s[44:45]
	v_ashrrev_i32_e32 v71, 31, v70
	v_mad_i64_i32 v[74:75], s[0:1], v70, s81, v[72:73]
	v_mov_b32_e32 v79, v1
	v_mov_b32_e32 v78, v36
	v_lshl_add_u64 v[80:81], v[74:75], 0, v[78:79]
	v_mad_i64_i32 v[74:75], s[0:1], v70, s84, v[34:35]
	v_lshlrev_b64 v[82:83], 11, v[70:71]
	v_lshl_add_u64 v[84:85], v[32:33], 0, v[82:83]
	v_add_co_u32_e32 v82, vcc, s83, v80
	global_load_dwordx4 v[86:89], v[84:85], off offset:1536
	s_nop 0
	v_addc_co_u32_e32 v83, vcc, 0, v81, vcc
	global_load_dwordx4 v[90:93], v[74:75], off offset:1024
	global_load_dwordx4 v[94:97], v[82:83], off offset:1536
	v_add_u32_e32 v74, 2, v70
	v_ashrrev_i32_e32 v75, 31, v74
	v_mad_i64_i32 v[80:81], s[0:1], v74, s84, v[34:35]
	v_lshlrev_b64 v[82:83], 11, v[74:75]
	v_mad_i64_i32 v[98:99], s[0:1], v74, s81, v[72:73]
	v_lshl_add_u64 v[74:75], v[98:99], 0, v[78:79]
	v_lshl_add_u64 v[98:99], v[32:33], 0, v[82:83]
	v_add_co_u32_e32 v82, vcc, s83, v74
	global_load_dwordx4 v[100:103], v[98:99], off offset:1536
	s_nop 0
	v_addc_co_u32_e32 v83, vcc, 0, v75, vcc
	global_load_dwordx4 v[104:107], v[80:81], off offset:1024
	global_load_dwordx4 v[108:111], v[82:83], off offset:1536
	v_add_u32_e32 v74, 4, v70
	v_ashrrev_i32_e32 v75, 31, v74
	v_mad_i64_i32 v[80:81], s[0:1], v74, s84, v[34:35]
	v_lshlrev_b64 v[82:83], 11, v[74:75]
	v_mad_i64_i32 v[112:113], s[0:1], v74, s81, v[72:73]
	v_lshl_add_u64 v[74:75], v[112:113], 0, v[78:79]
	v_lshl_add_u64 v[112:113], v[32:33], 0, v[82:83]
	v_add_co_u32_e32 v82, vcc, s83, v74
	global_load_dwordx4 v[114:117], v[112:113], off offset:1536
	s_nop 0
	v_addc_co_u32_e32 v83, vcc, 0, v75, vcc
	global_load_dwordx4 v[118:121], v[80:81], off offset:1024
	global_load_dwordx4 v[122:125], v[82:83], off offset:1536
	v_add_u32_e32 v74, 6, v70
	v_ashrrev_i32_e32 v75, 31, v74
	v_mad_i64_i32 v[70:71], s[0:1], v74, s81, v[72:73]
	v_lshlrev_b64 v[72:73], 11, v[74:75]
	v_lshl_add_u64 v[80:81], v[70:71], 0, v[78:79]
	v_lshl_add_u64 v[70:71], v[32:33], 0, v[72:73]
	v_mad_i64_i32 v[72:73], s[0:1], v74, s84, v[34:35]
	v_add_co_u32_e32 v74, vcc, s83, v80
	global_load_dwordx4 v[126:129], v[70:71], off offset:1536
	s_nop 0
	v_addc_co_u32_e32 v75, vcc, 0, v81, vcc
	global_load_dwordx4 v[78:81], v[72:73], off offset:1024
	global_load_dwordx4 v[130:133], v[74:75], off offset:1536
	s_nop 0
	s_waitcnt vmcnt(27)
; __device__ __forceinline__ unsigned pk2(float lo, float hi) { const f32v2_t f = {lo, hi}; const bf16v2_t b = __builtin_convertvector(f, bf16v2_t); return __builtin_bit_cast(unsigned, b); }
; __device__ __forceinline__ float siluf(float v) { return v * __builtin_amdgcn_rcpf(1.f + __expf(-v)); }
; __device__ NOINL void combine_phase(const LAS Params* lp, int l, LAS unsigned char* lds) {
;     ...
;         for (int i = 0; i < 8; ++i) {
;             const size_t row = (size_t)(row0 + 8 * w + i);
;             float of[8], ob[8], zz[8];
;             unpack8(*(const u32x4*)(p.hbuf + row * DM + 256 + lane * 8), of); unpack8(*(const u32x4*)(p.hyproj + row * 768 + lane * 8), ob); unpack8(*(const u32x4*)(p.proj + row * 3072 + 1536 + lane * 8), zz);
;             float ss = 0.f;
; #pragma unroll
;             for (int e = 0; e < 8; ++e) { of[e] += ob[e]; ss += of[e] * of[e]; }
;             ss += __shfl_xor(ss, 1); ss += __shfl_xor(ss, 2); ss += __shfl_xor(ss, 4); ss += __shfl_xor(ss, 8);
;             const float inv = rsqrtf(ss * (1.f / 128.f) + 1e-6f);
;             float o[8];
; #pragma unroll
;             for (int e = 0; e < 8; ++e) o[e] = of[e] * inv * ng8[e] * siluf(zz[e]);
;             u32x4 pk; pk.x = pk2(o[0], o[1]); pk.y = pk2(o[2], o[3]); pk.z = pk2(o[4], o[5]); pk.w = pk2(o[6], o[7]);
;             *(u32x4*)(p.hbuf + row * DM + 256 + lane * 8) = pk;
	v_lshlrev_b32_e32 v38, 16, v139
	v_and_b32_e32 v39, 0xffff0000, v139
	v_lshlrev_b32_e32 v62, 16, v138
	v_and_b32_e32 v63, 0xffff0000, v138
	s_waitcnt vmcnt(26)
	v_lshlrev_b32_e32 v66, 16, v141
	v_and_b32_e32 v67, 0xffff0000, v141
	v_lshlrev_b32_e32 v60, 16, v143
	v_and_b32_e32 v61, 0xffff0000, v143
	s_waitcnt vmcnt(25)
	v_lshlrev_b32_e32 v18, 16, v146
	v_and_b32_e32 v19, 0xffff0000, v146
	v_lshlrev_b32_e32 v42, 16, v142
	v_mul_f32_e32 v21, 0xbfb8aa3b, v42
	v_exp_f32_e32 v21, v21
	v_lshlrev_b32_e32 v44, 16, v147
	v_and_b32_e32 v45, 0xffff0000, v147
	v_and_b32_e32 v43, 0xffff0000, v142
	v_add_f32_e32 v21, 1.0, v21
	v_pk_add_f32 v[18:19], v[62:63], v[18:19]
	v_rcp_f32_e32 v62, v21
	v_mul_f32_e32 v21, 0xbfb8aa3b, v43
	v_exp_f32_e32 v21, v21
	v_lshlrev_b32_e32 v64, 16, v145
	v_and_b32_e32 v65, 0xffff0000, v145
	v_and_b32_e32 v41, 0xffff0000, v140
	v_add_f32_e32 v21, 1.0, v21
	v_rcp_f32_e32 v63, v21
	v_pk_mul_f32 v[58:59], v[18:19], v[18:19]
	v_pk_add_f32 v[38:39], v[38:39], v[44:45]
	v_pk_mul_f32 v[42:43], v[62:63], v[42:43]
	v_lshlrev_b32_e32 v62, 16, v137
	v_and_b32_e32 v63, 0xffff0000, v137
	v_mul_f32_e32 v17, 0xbfb8aa3b, v66
	v_exp_f32_e32 v17, v17
	v_pk_add_f32 v[62:63], v[62:63], v[64:65]
	v_pk_mul_f32 v[44:45], v[38:39], v[38:39]
	v_pk_mul_f32 v[64:65], v[62:63], v[62:63]
	v_add_f32_e32 v17, 1.0, v17
	v_rcp_f32_e32 v68, v17
	v_mul_f32_e32 v17, 0xbfb8aa3b, v67
	v_exp_f32_e32 v17, v17
	s_nop 0
	v_add_f32_e32 v17, 1.0, v17
	v_rcp_f32_e32 v69, v17
	v_and_b32_e32 v17, 0xffff0000, v144
	v_pk_mul_f32 v[66:67], v[68:69], v[66:67]
	v_lshlrev_b32_e32 v68, 16, v136
	v_and_b32_e32 v69, 0xffff0000, v136
	v_lshlrev_b32_e32 v16, 16, v144
	v_lshlrev_b32_e32 v40, 16, v140
	v_mul_f32_e32 v21, 0xbfb8aa3b, v40
	v_exp_f32_e32 v21, v21
	v_pk_add_f32 v[16:17], v[68:69], v[16:17]
	v_add_f32_e32 v21, 1.0, v21
	v_rcp_f32_e32 v68, v21
	v_mul_f32_e32 v21, 0xbfb8aa3b, v41
	v_exp_f32_e32 v21, v21
	v_pk_mul_f32 v[56:57], v[16:17], v[16:17]
	v_add_f32_e32 v21, 1.0, v21
	v_rcp_f32_e32 v69, v21
	v_add_f32_e32 v21, v56, v57
	v_add_f32_e32 v21, v64, v21
	v_add_f32_e32 v21, v65, v21
	v_add_f32_e32 v21, v58, v21
	v_add_f32_e32 v21, v59, v21
	v_add_f32_e32 v21, v44, v21
	v_add_f32_e32 v21, v45, v21
	ds_bpermute_b32 v37, v49, v21
	v_pk_mul_f32 v[40:41], v[68:69], v[40:41]
	s_waitcnt lgkmcnt(0)
	v_add_f32_e32 v21, v21, v37
	ds_bpermute_b32 v37, v50, v21
	s_waitcnt lgkmcnt(0)
	v_add_f32_e32 v21, v21, v37
	ds_bpermute_b32 v37, v51, v21
	s_waitcnt lgkmcnt(0)
	v_add_f32_e32 v21, v21, v37
	ds_bpermute_b32 v37, v52, v21
	s_waitcnt lgkmcnt(0)
	v_add_f32_e32 v21, v21, v37
	v_fmamk_f32 v21, v21, 0x3c000000, v211
	v_cmp_gt_f32_e32 vcc, s79, v21
	v_mul_f32_e32 v37, 0x4b800000, v21
	s_nop 0
	v_cndmask_b32_e32 v21, v21, v37, vcc
	v_rsq_f32_e32 v21, v21
	s_nop 0
	v_mul_f32_e32 v37, 0x45800000, v21
	v_cndmask_b32_e32 v44, v21, v37, vcc
	v_mul_f32_e32 v21, 0xbfb8aa3b, v60
	v_exp_f32_e32 v21, v21
	v_pk_mul_f32 v[18:19], v[18:19], v[44:45] op_sel_hi:[1,0]
	v_pk_mul_f32 v[16:17], v[16:17], v[44:45] op_sel_hi:[1,0]
	v_pk_mul_f32 v[18:19], v[8:9], v[18:19]
	v_add_f32_e32 v21, 1.0, v21
	v_pk_mul_f32 v[18:19], v[42:43], v[18:19]
	v_rcp_f32_e32 v42, v21
	v_mul_f32_e32 v21, 0xbfb8aa3b, v61
	v_exp_f32_e32 v21, v21
	v_pk_mul_f32 v[16:17], v[12:13], v[16:17]
	v_pk_mul_f32 v[38:39], v[38:39], v[44:45] op_sel_hi:[1,0]
	v_pk_mul_f32 v[16:17], v[40:41], v[16:17]
	v_add_f32_e32 v21, 1.0, v21
	v_rcp_f32_e32 v43, v21
	v_pk_mul_f32 v[40:41], v[62:63], v[44:45] op_sel_hi:[1,0]
	v_pk_mul_f32 v[38:39], v[10:11], v[38:39]
	v_pk_mul_f32 v[40:41], v[14:15], v[40:41]
	v_pk_mul_f32 v[42:43], v[42:43], v[60:61]
	v_pk_mul_f32 v[40:41], v[66:67], v[40:41]
	v_pk_mul_f32 v[38:39], v[42:43], v[38:39]
	v_cvt_pk_bf16_f32 v18, v18, v19
	v_cvt_pk_bf16_f32 v19, v38, v39
	v_cvt_pk_bf16_f32 v16, v16, v17
	v_cvt_pk_bf16_f32 v17, v40, v41
	global_store_dwordx4 v[134:135], v[16:19], off offset:512
	s_nop 0
	s_waitcnt vmcnt(25)
	v_lshlrev_b32_e32 v38, 16, v153
	v_and_b32_e32 v39, 0xffff0000, v153
	v_lshlrev_b32_e32 v62, 16, v152
	v_and_b32_e32 v63, 0xffff0000, v152
	s_waitcnt vmcnt(24)
	v_lshlrev_b32_e32 v66, 16, v155
	v_and_b32_e32 v67, 0xffff0000, v155
	v_lshlrev_b32_e32 v60, 16, v157
	v_and_b32_e32 v61, 0xffff0000, v157
	s_waitcnt vmcnt(23)
	v_lshlrev_b32_e32 v18, 16, v160
	v_and_b32_e32 v19, 0xffff0000, v160
	v_lshlrev_b32_e32 v42, 16, v156
	v_mul_f32_e32 v21, 0xbfb8aa3b, v42
	v_exp_f32_e32 v21, v21
	v_lshlrev_b32_e32 v44, 16, v161
	v_and_b32_e32 v45, 0xffff0000, v161
	v_and_b32_e32 v43, 0xffff0000, v156
	v_add_f32_e32 v21, 1.0, v21
	v_pk_add_f32 v[18:19], v[62:63], v[18:19]
	v_rcp_f32_e32 v62, v21
	v_mul_f32_e32 v21, 0xbfb8aa3b, v43
	v_exp_f32_e32 v21, v21
	v_lshlrev_b32_e32 v64, 16, v159
	v_and_b32_e32 v65, 0xffff0000, v159
	v_and_b32_e32 v41, 0xffff0000, v154
	v_add_f32_e32 v21, 1.0, v21
	v_rcp_f32_e32 v63, v21
	v_pk_mul_f32 v[58:59], v[18:19], v[18:19]
	v_pk_add_f32 v[38:39], v[38:39], v[44:45]
	v_pk_mul_f32 v[42:43], v[62:63], v[42:43]
	v_lshlrev_b32_e32 v62, 16, v151
	v_and_b32_e32 v63, 0xffff0000, v151
	v_mul_f32_e32 v17, 0xbfb8aa3b, v66
	v_exp_f32_e32 v17, v17
	v_pk_add_f32 v[62:63], v[62:63], v[64:65]
	v_pk_mul_f32 v[44:45], v[38:39], v[38:39]
	v_pk_mul_f32 v[64:65], v[62:63], v[62:63]
	v_add_f32_e32 v17, 1.0, v17
	v_rcp_f32_e32 v68, v17
	v_mul_f32_e32 v17, 0xbfb8aa3b, v67
	v_exp_f32_e32 v17, v17
	s_nop 0
	v_add_f32_e32 v17, 1.0, v17
	v_rcp_f32_e32 v69, v17
	v_and_b32_e32 v17, 0xffff0000, v158
	v_pk_mul_f32 v[66:67], v[68:69], v[66:67]
	v_lshlrev_b32_e32 v68, 16, v150
	v_and_b32_e32 v69, 0xffff0000, v150
	v_lshlrev_b32_e32 v16, 16, v158
	v_lshlrev_b32_e32 v40, 16, v154
	v_mul_f32_e32 v21, 0xbfb8aa3b, v40
	v_exp_f32_e32 v21, v21
	v_pk_add_f32 v[16:17], v[68:69], v[16:17]
	v_add_f32_e32 v21, 1.0, v21
	v_rcp_f32_e32 v68, v21
	v_mul_f32_e32 v21, 0xbfb8aa3b, v41
	v_exp_f32_e32 v21, v21
	v_pk_mul_f32 v[56:57], v[16:17], v[16:17]
	v_add_f32_e32 v21, 1.0, v21
	v_rcp_f32_e32 v69, v21
	v_add_f32_e32 v21, v56, v57
	v_add_f32_e32 v21, v64, v21
	v_add_f32_e32 v21, v65, v21
	v_add_f32_e32 v21, v58, v21
	v_add_f32_e32 v21, v59, v21
	v_add_f32_e32 v21, v44, v21
	v_add_f32_e32 v21, v45, v21
	ds_bpermute_b32 v37, v49, v21
	v_pk_mul_f32 v[40:41], v[68:69], v[40:41]
	s_waitcnt lgkmcnt(0)
; __device__ __forceinline__ unsigned pk2(float lo, float hi) { const f32v2_t f = {lo, hi}; const bf16v2_t b = __builtin_convertvector(f, bf16v2_t); return __builtin_bit_cast(unsigned, b); }
; __device__ __forceinline__ float siluf(float v) { return v * __builtin_amdgcn_rcpf(1.f + __expf(-v)); }
; __device__ NOINL void combine_phase(const LAS Params* lp, int l, LAS unsigned char* lds) {
;     ...
;         for (int i = 0; i < 8; ++i) {
;             const size_t row = (size_t)(row0 + 8 * w + i);
;             float of[8], ob[8], zz[8];
;             unpack8(*(const u32x4*)(p.hbuf + row * DM + 256 + lane * 8), of); unpack8(*(const u32x4*)(p.hyproj + row * 768 + lane * 8), ob); unpack8(*(const u32x4*)(p.proj + row * 3072 + 1536 + lane * 8), zz);
;             float ss = 0.f;
; #pragma unroll
;             for (int e = 0; e < 8; ++e) { of[e] += ob[e]; ss += of[e] * of[e]; }
;             ss += __shfl_xor(ss, 1); ss += __shfl_xor(ss, 2); ss += __shfl_xor(ss, 4); ss += __shfl_xor(ss, 8);
;             const float inv = rsqrtf(ss * (1.f / 128.f) + 1e-6f);
;             float o[8];
; #pragma unroll
;             for (int e = 0; e < 8; ++e) o[e] = of[e] * inv * ng8[e] * siluf(zz[e]);
;             u32x4 pk; pk.x = pk2(o[0], o[1]); pk.y = pk2(o[2], o[3]); pk.z = pk2(o[4], o[5]); pk.w = pk2(o[6], o[7]);
;             *(u32x4*)(p.hbuf + row * DM + 256 + lane * 8) = pk;
	v_add_f32_e32 v21, v21, v37
	ds_bpermute_b32 v37, v50, v21
	s_waitcnt lgkmcnt(0)
	v_add_f32_e32 v21, v21, v37
	ds_bpermute_b32 v37, v51, v21
	s_waitcnt lgkmcnt(0)
	v_add_f32_e32 v21, v21, v37
	ds_bpermute_b32 v37, v52, v21
	s_waitcnt lgkmcnt(0)
	v_add_f32_e32 v21, v21, v37
	v_fmamk_f32 v21, v21, 0x3c000000, v211
	v_cmp_gt_f32_e32 vcc, s79, v21
	v_mul_f32_e32 v37, 0x4b800000, v21
	s_nop 0
	v_cndmask_b32_e32 v21, v21, v37, vcc
	v_rsq_f32_e32 v21, v21
	s_nop 0
	v_mul_f32_e32 v37, 0x45800000, v21
	v_cndmask_b32_e32 v44, v21, v37, vcc
	v_mul_f32_e32 v21, 0xbfb8aa3b, v60
	v_exp_f32_e32 v21, v21
	v_pk_mul_f32 v[18:19], v[18:19], v[44:45] op_sel_hi:[1,0]
	v_pk_mul_f32 v[16:17], v[16:17], v[44:45] op_sel_hi:[1,0]
	v_pk_mul_f32 v[18:19], v[8:9], v[18:19]
	v_add_f32_e32 v21, 1.0, v21
	v_pk_mul_f32 v[18:19], v[42:43], v[18:19]
	v_rcp_f32_e32 v42, v21
	v_mul_f32_e32 v21, 0xbfb8aa3b, v61
	v_exp_f32_e32 v21, v21
	v_pk_mul_f32 v[16:17], v[12:13], v[16:17]
	v_pk_mul_f32 v[38:39], v[38:39], v[44:45] op_sel_hi:[1,0]
	v_pk_mul_f32 v[16:17], v[40:41], v[16:17]
	v_add_f32_e32 v21, 1.0, v21
	v_rcp_f32_e32 v43, v21
	v_pk_mul_f32 v[40:41], v[62:63], v[44:45] op_sel_hi:[1,0]
	v_pk_mul_f32 v[38:39], v[10:11], v[38:39]
	v_pk_mul_f32 v[40:41], v[14:15], v[40:41]
	v_pk_mul_f32 v[42:43], v[42:43], v[60:61]
	v_pk_mul_f32 v[40:41], v[66:67], v[40:41]
	v_pk_mul_f32 v[38:39], v[42:43], v[38:39]
	v_cvt_pk_bf16_f32 v18, v18, v19
	v_cvt_pk_bf16_f32 v19, v38, v39
	v_cvt_pk_bf16_f32 v16, v16, v17
	v_cvt_pk_bf16_f32 v17, v40, v41
	global_store_dwordx4 v[148:149], v[16:19], off offset:512
	s_nop 0
	s_waitcnt vmcnt(23)
	v_lshlrev_b32_e32 v38, 16, v167
	v_and_b32_e32 v39, 0xffff0000, v167
	v_lshlrev_b32_e32 v62, 16, v166
	v_and_b32_e32 v63, 0xffff0000, v166
	s_waitcnt vmcnt(22)
	v_lshlrev_b32_e32 v66, 16, v169
	v_and_b32_e32 v67, 0xffff0000, v169
	v_lshlrev_b32_e32 v60, 16, v171
	v_and_b32_e32 v61, 0xffff0000, v171
	s_waitcnt vmcnt(21)
	v_lshlrev_b32_e32 v18, 16, v174
	v_and_b32_e32 v19, 0xffff0000, v174
	v_lshlrev_b32_e32 v42, 16, v170
	v_mul_f32_e32 v21, 0xbfb8aa3b, v42
	v_exp_f32_e32 v21, v21
	v_lshlrev_b32_e32 v44, 16, v175
	v_and_b32_e32 v45, 0xffff0000, v175
	v_and_b32_e32 v43, 0xffff0000, v170
	v_add_f32_e32 v21, 1.0, v21
	v_pk_add_f32 v[18:19], v[62:63], v[18:19]
	v_rcp_f32_e32 v62, v21
	v_mul_f32_e32 v21, 0xbfb8aa3b, v43
	v_exp_f32_e32 v21, v21
	v_lshlrev_b32_e32 v64, 16, v173
	v_and_b32_e32 v65, 0xffff0000, v173
	v_and_b32_e32 v41, 0xffff0000, v168
	v_add_f32_e32 v21, 1.0, v21
	v_rcp_f32_e32 v63, v21
	v_pk_mul_f32 v[58:59], v[18:19], v[18:19]
	v_pk_add_f32 v[38:39], v[38:39], v[44:45]
	v_pk_mul_f32 v[42:43], v[62:63], v[42:43]
	v_lshlrev_b32_e32 v62, 16, v165
	v_and_b32_e32 v63, 0xffff0000, v165
	v_mul_f32_e32 v17, 0xbfb8aa3b, v66
	v_exp_f32_e32 v17, v17
	v_pk_add_f32 v[62:63], v[62:63], v[64:65]
	v_pk_mul_f32 v[44:45], v[38:39], v[38:39]
	v_pk_mul_f32 v[64:65], v[62:63], v[62:63]
	v_add_f32_e32 v17, 1.0, v17
	v_rcp_f32_e32 v68, v17
	v_mul_f32_e32 v17, 0xbfb8aa3b, v67
	v_exp_f32_e32 v17, v17
	s_nop 0
	v_add_f32_e32 v17, 1.0, v17
	v_rcp_f32_e32 v69, v17
	v_and_b32_e32 v17, 0xffff0000, v172
	v_pk_mul_f32 v[66:67], v[68:69], v[66:67]
	v_lshlrev_b32_e32 v68, 16, v164
	v_and_b32_e32 v69, 0xffff0000, v164
	v_lshlrev_b32_e32 v16, 16, v172
	v_lshlrev_b32_e32 v40, 16, v168
	v_mul_f32_e32 v21, 0xbfb8aa3b, v40
	v_exp_f32_e32 v21, v21
	v_pk_add_f32 v[16:17], v[68:69], v[16:17]
	v_add_f32_e32 v21, 1.0, v21
	v_rcp_f32_e32 v68, v21
	v_mul_f32_e32 v21, 0xbfb8aa3b, v41
	v_exp_f32_e32 v21, v21
	v_pk_mul_f32 v[56:57], v[16:17], v[16:17]
	v_add_f32_e32 v21, 1.0, v21
	v_rcp_f32_e32 v69, v21
	v_add_f32_e32 v21, v56, v57
	v_add_f32_e32 v21, v64, v21
	v_add_f32_e32 v21, v65, v21
	v_add_f32_e32 v21, v58, v21
	v_add_f32_e32 v21, v59, v21
	v_add_f32_e32 v21, v44, v21
	v_add_f32_e32 v21, v45, v21
	ds_bpermute_b32 v37, v49, v21
	v_pk_mul_f32 v[40:41], v[68:69], v[40:41]
	s_waitcnt lgkmcnt(0)
	v_add_f32_e32 v21, v21, v37
	ds_bpermute_b32 v37, v50, v21
	s_waitcnt lgkmcnt(0)
	v_add_f32_e32 v21, v21, v37
	ds_bpermute_b32 v37, v51, v21
	s_waitcnt lgkmcnt(0)
	v_add_f32_e32 v21, v21, v37
	ds_bpermute_b32 v37, v52, v21
	s_waitcnt lgkmcnt(0)
	v_add_f32_e32 v21, v21, v37
	v_fmamk_f32 v21, v21, 0x3c000000, v211
	v_cmp_gt_f32_e32 vcc, s79, v21
	v_mul_f32_e32 v37, 0x4b800000, v21
	s_nop 0
	v_cndmask_b32_e32 v21, v21, v37, vcc
	v_rsq_f32_e32 v21, v21
	s_nop 0
	v_mul_f32_e32 v37, 0x45800000, v21
	v_cndmask_b32_e32 v44, v21, v37, vcc
	v_mul_f32_e32 v21, 0xbfb8aa3b, v60
	v_exp_f32_e32 v21, v21
	v_pk_mul_f32 v[18:19], v[18:19], v[44:45] op_sel_hi:[1,0]
	v_pk_mul_f32 v[16:17], v[16:17], v[44:45] op_sel_hi:[1,0]
	v_pk_mul_f32 v[18:19], v[8:9], v[18:19]
	v_add_f32_e32 v21, 1.0, v21
	v_pk_mul_f32 v[18:19], v[42:43], v[18:19]
	v_rcp_f32_e32 v42, v21
	v_mul_f32_e32 v21, 0xbfb8aa3b, v61
	v_exp_f32_e32 v21, v21
	v_pk_mul_f32 v[16:17], v[12:13], v[16:17]
	v_pk_mul_f32 v[38:39], v[38:39], v[44:45] op_sel_hi:[1,0]
	v_pk_mul_f32 v[16:17], v[40:41], v[16:17]
	v_add_f32_e32 v21, 1.0, v21
	v_rcp_f32_e32 v43, v21
	v_pk_mul_f32 v[40:41], v[62:63], v[44:45] op_sel_hi:[1,0]
	v_pk_mul_f32 v[38:39], v[10:11], v[38:39]
	v_pk_mul_f32 v[40:41], v[14:15], v[40:41]
	v_pk_mul_f32 v[42:43], v[42:43], v[60:61]
	v_pk_mul_f32 v[40:41], v[66:67], v[40:41]
	v_pk_mul_f32 v[38:39], v[42:43], v[38:39]
	v_cvt_pk_bf16_f32 v16, v16, v17
	v_cvt_pk_bf16_f32 v17, v40, v41
	v_cvt_pk_bf16_f32 v18, v18, v19
	v_cvt_pk_bf16_f32 v19, v38, v39
	global_store_dwordx4 v[162:163], v[16:19], off offset:512
	s_waitcnt vmcnt(21)
	v_lshlrev_b32_e32 v22, 16, v179
	v_and_b32_e32 v23, 0xffff0000, v179
	v_lshlrev_b32_e32 v60, 16, v178
	v_and_b32_e32 v61, 0xffff0000, v178
	s_waitcnt vmcnt(20)
; __device__ __forceinline__ unsigned pk2(float lo, float hi) { const f32v2_t f = {lo, hi}; const bf16v2_t b = __builtin_convertvector(f, bf16v2_t); return __builtin_bit_cast(unsigned, b); }
; __device__ NOINL void combine_phase(const LAS Params* lp, int l, LAS unsigned char* lds) {
;     ...
;         for (int i = 0; i < 8; ++i) {
;             const size_t row = (size_t)(row0 + 8 * w + i);
;             float of[8], ob[8], zz[8];
;             unpack8(*(const u32x4*)(p.hbuf + row * DM + 256 + lane * 8), of); unpack8(*(const u32x4*)(p.hyproj + row * 768 + lane * 8), ob); unpack8(*(const u32x4*)(p.proj + row * 3072 + 1536 + lane * 8), zz);
;             float ss = 0.f;
; #pragma unroll
;             for (int e = 0; e < 8; ++e) { of[e] += ob[e]; ss += of[e] * of[e]; }
;             ss += __shfl_xor(ss, 1); ss += __shfl_xor(ss, 2); ss += __shfl_xor(ss, 4); ss += __shfl_xor(ss, 8);
;             const float inv = rsqrtf(ss * (1.f / 128.f) + 1e-6f);
;             float o[8];
; #pragma unroll
;             for (int e = 0; e < 8; ++e) o[e] = of[e] * inv * ng8[e] * siluf(zz[e]);
;             u32x4 pk; pk.x = pk2(o[0], o[1]); pk.y = pk2(o[2], o[3]); pk.z = pk2(o[4], o[5]); pk.w = pk2(o[6], o[7]);
;             *(u32x4*)(p.hbuf + row * DM + 256 + lane * 8) = pk;
;         }
; #pragma unroll
;         for (int i = 0; i < 4; ++i) {
;             const size_t row = (size_t)(row0 + 8 * w + 2 * i + (lane >> 5)); const int l32 = lane & 31;
;             float of[8], ob[8], gg[8];
;             unpack8(*(const u32x4*)(p.hbuf + row * DM + 768 + l32 * 8), of); unpack8(*(const u32x4*)(p.hyproj + row * 768 + 512 + l32 * 8), ob); unpack8(*(const u32x4*)(p.proj + row * 3072 + 2816 + l32 * 8), gg);
;             float s1 = 0.f;
; #pragma unroll
;             for (int e = 0; e < 8; ++e) { of[e] += ob[e]; s1 += of[e]; }
;             s1 += __shfl_xor(s1, 1); s1 += __shfl_xor(s1, 2); s1 += __shfl_xor(s1, 4);
;             const float mu = s1 * (1.f / 64.f); float s2 = 0.f;
; #pragma unroll
;             for (int e = 0; e < 8; ++e) { of[e] -= mu; s2 += of[e] * of[e]; }
;             s2 += __shfl_xor(s2, 1); s2 += __shfl_xor(s2, 2); s2 += __shfl_xor(s2, 4);
;             const float inv = rsqrtf(s2 * (1.f / 64.f) + 1e-6f);
;             float o[8];
; #pragma unroll
;             for (int e = 0; e < 8; ++e) o[e] = of[e] * inv * siluf(gg[e]);
	v_lshlrev_b32_e32 v64, 16, v181
	v_and_b32_e32 v65, 0xffff0000, v181
	v_lshlrev_b32_e32 v58, 16, v183
	v_and_b32_e32 v59, 0xffff0000, v183
	s_waitcnt vmcnt(19)
	v_lshlrev_b32_e32 v18, 16, v188
	v_and_b32_e32 v19, 0xffff0000, v188
	v_lshlrev_b32_e32 v40, 16, v182
	v_mul_f32_e32 v37, 0xbfb8aa3b, v40
	v_exp_f32_e32 v37, v37
	v_lshlrev_b32_e32 v56, 16, v189
	v_and_b32_e32 v57, 0xffff0000, v189
	v_and_b32_e32 v41, 0xffff0000, v182
	v_add_f32_e32 v37, 1.0, v37
	v_pk_add_f32 v[18:19], v[60:61], v[18:19]
	v_rcp_f32_e32 v60, v37
	v_mul_f32_e32 v37, 0xbfb8aa3b, v41
	v_exp_f32_e32 v37, v37
	v_lshlrev_b32_e32 v62, 16, v187
	v_and_b32_e32 v63, 0xffff0000, v187
	v_and_b32_e32 v39, 0xffff0000, v180
	v_add_f32_e32 v37, 1.0, v37
	v_rcp_f32_e32 v61, v37
	v_pk_mul_f32 v[44:45], v[18:19], v[18:19]
	v_pk_add_f32 v[22:23], v[22:23], v[56:57]
	v_pk_mul_f32 v[40:41], v[60:61], v[40:41]
	v_lshlrev_b32_e32 v60, 16, v177
	v_and_b32_e32 v61, 0xffff0000, v177
	v_mul_f32_e32 v17, 0xbfb8aa3b, v64
	v_exp_f32_e32 v17, v17
	v_pk_add_f32 v[60:61], v[60:61], v[62:63]
	v_pk_mul_f32 v[56:57], v[22:23], v[22:23]
	v_pk_mul_f32 v[62:63], v[60:61], v[60:61]
	v_add_f32_e32 v17, 1.0, v17
	v_rcp_f32_e32 v66, v17
	v_mul_f32_e32 v17, 0xbfb8aa3b, v65
	v_exp_f32_e32 v17, v17
	s_nop 0
	v_add_f32_e32 v17, 1.0, v17
	v_rcp_f32_e32 v67, v17
	v_and_b32_e32 v17, 0xffff0000, v186
	v_pk_mul_f32 v[64:65], v[66:67], v[64:65]
	v_lshlrev_b32_e32 v66, 16, v176
	v_and_b32_e32 v67, 0xffff0000, v176
	v_lshlrev_b32_e32 v16, 16, v186
	v_lshlrev_b32_e32 v38, 16, v180
	v_mul_f32_e32 v37, 0xbfb8aa3b, v38
	v_exp_f32_e32 v37, v37
	v_pk_add_f32 v[16:17], v[66:67], v[16:17]
	v_add_f32_e32 v37, 1.0, v37
	v_rcp_f32_e32 v66, v37
	v_mul_f32_e32 v37, 0xbfb8aa3b, v39
	v_exp_f32_e32 v37, v37
	v_pk_mul_f32 v[42:43], v[16:17], v[16:17]
	v_add_f32_e32 v37, 1.0, v37
	v_rcp_f32_e32 v67, v37
	v_add_f32_e32 v37, v42, v43
	v_add_f32_e32 v37, v62, v37
	v_add_f32_e32 v37, v63, v37
	v_add_f32_e32 v37, v44, v37
	v_add_f32_e32 v37, v45, v37
	v_add_f32_e32 v37, v56, v37
	v_add_f32_e32 v37, v57, v37
	ds_bpermute_b32 v42, v49, v37
	v_pk_mul_f32 v[38:39], v[66:67], v[38:39]
	s_waitcnt lgkmcnt(0)
	v_add_f32_e32 v37, v37, v42
	ds_bpermute_b32 v42, v50, v37
	s_waitcnt lgkmcnt(0)
	v_add_f32_e32 v37, v37, v42
	ds_bpermute_b32 v42, v51, v37
	s_waitcnt lgkmcnt(0)
	v_add_f32_e32 v37, v37, v42
	ds_bpermute_b32 v42, v52, v37
	s_waitcnt lgkmcnt(0)
	v_add_f32_e32 v37, v37, v42
	v_fmamk_f32 v37, v37, 0x3c000000, v211
	v_cmp_gt_f32_e32 vcc, s79, v37
	v_mul_f32_e32 v42, 0x4b800000, v37
	s_nop 0
	v_cndmask_b32_e32 v37, v37, v42, vcc
	v_rsq_f32_e32 v37, v37
	s_nop 0
	v_mul_f32_e32 v42, 0x45800000, v37
	v_cndmask_b32_e32 v42, v37, v42, vcc
	v_mul_f32_e32 v37, 0xbfb8aa3b, v58
	v_exp_f32_e32 v37, v37
	v_pk_mul_f32 v[18:19], v[18:19], v[42:43] op_sel_hi:[1,0]
	v_pk_mul_f32 v[16:17], v[16:17], v[42:43] op_sel_hi:[1,0]
	v_pk_mul_f32 v[18:19], v[8:9], v[18:19]
	v_add_f32_e32 v37, 1.0, v37
	v_pk_mul_f32 v[18:19], v[40:41], v[18:19]
	v_rcp_f32_e32 v40, v37
	v_mul_f32_e32 v37, 0xbfb8aa3b, v59
	v_exp_f32_e32 v37, v37
	v_pk_mul_f32 v[16:17], v[12:13], v[16:17]
	v_pk_mul_f32 v[22:23], v[22:23], v[42:43] op_sel_hi:[1,0]
	v_pk_mul_f32 v[16:17], v[38:39], v[16:17]
	v_add_f32_e32 v37, 1.0, v37
	v_rcp_f32_e32 v41, v37
	v_pk_mul_f32 v[38:39], v[60:61], v[42:43] op_sel_hi:[1,0]
	v_pk_mul_f32 v[22:23], v[10:11], v[22:23]
	v_pk_mul_f32 v[38:39], v[14:15], v[38:39]
	v_pk_mul_f32 v[40:41], v[40:41], v[58:59]
	v_pk_mul_f32 v[38:39], v[64:65], v[38:39]
	v_pk_mul_f32 v[22:23], v[40:41], v[22:23]
	v_cvt_pk_bf16_f32 v16, v16, v17
	v_cvt_pk_bf16_f32 v17, v38, v39
	v_cvt_pk_bf16_f32 v18, v18, v19
	v_cvt_pk_bf16_f32 v19, v22, v23
	global_store_dwordx4 v[76:77], v[16:19], off offset:512
	s_nop 0
	s_waitcnt vmcnt(14)
	v_lshlrev_b32_e32 v60, 16, v93
	v_lshlrev_b32_e32 v44, 16, v89
	v_and_b32_e32 v45, 0xffff0000, v89
	v_and_b32_e32 v61, 0xffff0000, v93
	v_pk_add_f32 v[44:45], v[44:45], v[60:61]
	v_lshlrev_b32_e32 v60, 16, v88
	v_and_b32_e32 v61, 0xffff0000, v88
	v_lshlrev_b32_e32 v18, 16, v92
	v_and_b32_e32 v19, 0xffff0000, v92
	v_pk_add_f32 v[18:19], v[60:61], v[18:19]
	v_lshlrev_b32_e32 v60, 16, v91
	v_and_b32_e32 v61, 0xffff0000, v91
	s_waitcnt vmcnt(13)
	v_lshlrev_b32_e32 v22, 16, v96
	v_mul_f32_e32 v39, 0xbfb8aa3b, v22
	v_exp_f32_e32 v39, v39
	v_and_b32_e32 v23, 0xffff0000, v96
	v_lshlrev_b32_e32 v62, 16, v97
	v_and_b32_e32 v63, 0xffff0000, v97
	v_add_f32_e32 v39, 1.0, v39
	v_rcp_f32_e32 v58, v39
	v_mul_f32_e32 v39, 0xbfb8aa3b, v23
	v_exp_f32_e32 v39, v39
	v_lshlrev_b32_e32 v64, 16, v95
	v_and_b32_e32 v65, 0xffff0000, v95
	v_and_b32_e32 v21, 0xffff0000, v94
	v_add_f32_e32 v39, 1.0, v39
	v_rcp_f32_e32 v59, v39
	s_nop 0
	v_pk_mul_f32 v[22:23], v[58:59], v[22:23]
	v_lshlrev_b32_e32 v58, 16, v87
	v_and_b32_e32 v59, 0xffff0000, v87
	v_mul_f32_e32 v17, 0xbfb8aa3b, v64
	v_exp_f32_e32 v17, v17
	v_pk_add_f32 v[58:59], v[58:59], v[60:61]
	v_add_f32_e32 v17, 1.0, v17
	v_rcp_f32_e32 v60, v17
	v_mul_f32_e32 v17, 0xbfb8aa3b, v65
	v_exp_f32_e32 v17, v17
	s_nop 0
	v_add_f32_e32 v17, 1.0, v17
	v_rcp_f32_e32 v61, v17
	v_and_b32_e32 v17, 0xffff0000, v90
	v_pk_mul_f32 v[60:61], v[60:61], v[64:65]
	v_lshlrev_b32_e32 v64, 16, v86
	v_and_b32_e32 v65, 0xffff0000, v86
	v_lshlrev_b32_e32 v16, 16, v90
	v_lshlrev_b32_e32 v20, 16, v94
	v_mul_f32_e32 v55, 0xbfb8aa3b, v20
	v_exp_f32_e32 v55, v55
	v_pk_add_f32 v[16:17], v[64:65], v[16:17]
	v_add_f32_e32 v55, 1.0, v55
	v_add_f32_e32 v39, 0, v16
	v_add_f32_e32 v39, v17, v39
	v_rcp_f32_e32 v56, v55
	v_mul_f32_e32 v55, 0xbfb8aa3b, v21
	v_add_f32_e32 v39, v58, v39
	v_exp_f32_e32 v55, v55
	v_add_f32_e32 v39, v59, v39
	v_add_f32_e32 v39, v18, v39
	v_add_f32_e32 v39, v19, v39
	v_add_f32_e32 v39, v44, v39
	v_add_f32_e32 v55, 1.0, v55
	v_add_f32_e32 v39, v45, v39
	v_rcp_f32_e32 v57, v55
	ds_bpermute_b32 v55, v49, v39
	v_pk_mul_f32 v[20:21], v[56:57], v[20:21]
	s_waitcnt lgkmcnt(0)
; __device__ __forceinline__ unsigned pk2(float lo, float hi) { const f32v2_t f = {lo, hi}; const bf16v2_t b = __builtin_convertvector(f, bf16v2_t); return __builtin_bit_cast(unsigned, b); }
; __device__ __forceinline__ float siluf(float v) { return v * __builtin_amdgcn_rcpf(1.f + __expf(-v)); }
; __device__ NOINL void combine_phase(const LAS Params* lp, int l, LAS unsigned char* lds) {
;     ...
;         for (int i = 0; i < 4; ++i) {
;             const size_t row = (size_t)(row0 + 8 * w + 2 * i + (lane >> 5)); const int l32 = lane & 31;
;             float of[8], ob[8], gg[8];
;             unpack8(*(const u32x4*)(p.hbuf + row * DM + 768 + l32 * 8), of); unpack8(*(const u32x4*)(p.hyproj + row * 768 + 512 + l32 * 8), ob); unpack8(*(const u32x4*)(p.proj + row * 3072 + 2816 + l32 * 8), gg);
;             float s1 = 0.f;
; #pragma unroll
;             for (int e = 0; e < 8; ++e) { of[e] += ob[e]; s1 += of[e]; }
;             s1 += __shfl_xor(s1, 1); s1 += __shfl_xor(s1, 2); s1 += __shfl_xor(s1, 4);
;             const float mu = s1 * (1.f / 64.f); float s2 = 0.f;
; #pragma unroll
;             for (int e = 0; e < 8; ++e) { of[e] -= mu; s2 += of[e] * of[e]; }
;             s2 += __shfl_xor(s2, 1); s2 += __shfl_xor(s2, 2); s2 += __shfl_xor(s2, 4);
;             const float inv = rsqrtf(s2 * (1.f / 64.f) + 1e-6f);
;             float o[8];
; #pragma unroll
;             for (int e = 0; e < 8; ++e) o[e] = of[e] * inv * siluf(gg[e]);
;             u32x4 pk; pk.x = pk2(o[0], o[1]); pk.y = pk2(o[2], o[3]); pk.z = pk2(o[4], o[5]); pk.w = pk2(o[6], o[7]);
;             *(u32x4*)(p.hbuf + row * DM + 768 + l32 * 8) = pk;
	v_add_f32_e32 v39, v39, v55
	ds_bpermute_b32 v55, v50, v39
	s_waitcnt lgkmcnt(0)
	v_add_f32_e32 v39, v39, v55
	ds_bpermute_b32 v55, v51, v39
	s_waitcnt lgkmcnt(0)
	v_add_f32_e32 v39, v39, v55
	v_mul_f32_e32 v56, 0x3c800000, v39
	v_pk_add_f32 v[16:17], v[16:17], v[56:57] op_sel_hi:[1,0] neg_lo:[0,1] neg_hi:[0,1]
	v_pk_add_f32 v[58:59], v[58:59], v[56:57] op_sel_hi:[1,0] neg_lo:[0,1] neg_hi:[0,1]
	v_pk_mul_f32 v[64:65], v[16:17], v[16:17]
	v_pk_mul_f32 v[66:67], v[58:59], v[58:59]
	v_add_f32_e32 v39, v64, v65
	v_pk_add_f32 v[18:19], v[18:19], v[56:57] op_sel_hi:[1,0] neg_lo:[0,1] neg_hi:[0,1]
	v_add_f32_e32 v39, v66, v39
	v_pk_mul_f32 v[68:69], v[18:19], v[18:19]
	v_add_f32_e32 v39, v67, v39
	v_pk_add_f32 v[44:45], v[44:45], v[56:57] op_sel_hi:[1,0] neg_lo:[0,1] neg_hi:[0,1]
	v_add_f32_e32 v39, v68, v39
	v_pk_mul_f32 v[56:57], v[44:45], v[44:45]
	v_add_f32_e32 v39, v69, v39
	v_add_f32_e32 v39, v56, v39
	v_add_f32_e32 v39, v57, v39
	ds_bpermute_b32 v55, v49, v39
	s_waitcnt lgkmcnt(0)
	v_add_f32_e32 v39, v39, v55
	ds_bpermute_b32 v55, v50, v39
	s_waitcnt lgkmcnt(0)
	v_add_f32_e32 v39, v39, v55
	ds_bpermute_b32 v55, v51, v39
	s_waitcnt lgkmcnt(0)
	v_add_f32_e32 v39, v39, v55
	v_fmamk_f32 v39, v39, 0x3c800000, v211
	v_cmp_gt_f32_e32 vcc, s79, v39
	v_mul_f32_e32 v55, 0x4b800000, v39
	s_nop 0
	v_cndmask_b32_e32 v39, v39, v55, vcc
	v_rsq_f32_e32 v39, v39
	s_nop 0
	v_mul_f32_e32 v55, 0x45800000, v39
	v_cndmask_b32_e32 v56, v39, v55, vcc
	v_pk_mul_f32 v[18:19], v[18:19], v[56:57] op_sel_hi:[1,0]
	v_pk_mul_f32 v[16:17], v[16:17], v[56:57] op_sel_hi:[1,0]
	v_pk_mul_f32 v[18:19], v[22:23], v[18:19]
	v_mul_f32_e32 v22, 0xbfb8aa3b, v62
	v_mul_f32_e32 v23, 0xbfb8aa3b, v63
	v_exp_f32_e32 v22, v22
	v_exp_f32_e32 v23, v23
	v_pk_mul_f32 v[16:17], v[20:21], v[16:17]
	v_pk_mul_f32 v[20:21], v[58:59], v[56:57] op_sel_hi:[1,0]
	v_add_f32_e32 v22, 1.0, v22
	v_add_f32_e32 v23, 1.0, v23
	v_rcp_f32_e32 v22, v22
	v_rcp_f32_e32 v23, v23
	v_pk_mul_f32 v[44:45], v[44:45], v[56:57] op_sel_hi:[1,0]
	v_pk_mul_f32 v[20:21], v[60:61], v[20:21]
	v_cvt_pk_bf16_f32 v16, v16, v17
	v_pk_mul_f32 v[22:23], v[22:23], v[62:63]
	v_cvt_pk_bf16_f32 v17, v20, v21
	v_pk_mul_f32 v[22:23], v[22:23], v[44:45]
	v_cvt_pk_bf16_f32 v18, v18, v19
	v_cvt_pk_bf16_f32 v19, v22, v23
	global_store_dwordx4 v[84:85], v[16:19], off offset:1536
	s_nop 0
	s_nop 0
	s_waitcnt vmcnt(12)
	v_lshlrev_b32_e32 v60, 16, v107
	v_lshlrev_b32_e32 v44, 16, v103
	v_and_b32_e32 v45, 0xffff0000, v103
	v_and_b32_e32 v61, 0xffff0000, v107
	v_pk_add_f32 v[44:45], v[44:45], v[60:61]
	v_lshlrev_b32_e32 v60, 16, v102
	v_and_b32_e32 v61, 0xffff0000, v102
	v_lshlrev_b32_e32 v18, 16, v106
	v_and_b32_e32 v19, 0xffff0000, v106
	v_pk_add_f32 v[18:19], v[60:61], v[18:19]
	v_lshlrev_b32_e32 v60, 16, v105
	v_and_b32_e32 v61, 0xffff0000, v105
	s_waitcnt vmcnt(11)
	v_lshlrev_b32_e32 v22, 16, v110
	v_mul_f32_e32 v39, 0xbfb8aa3b, v22
	v_exp_f32_e32 v39, v39
	v_and_b32_e32 v23, 0xffff0000, v110
	v_lshlrev_b32_e32 v62, 16, v111
	v_and_b32_e32 v63, 0xffff0000, v111
	v_add_f32_e32 v39, 1.0, v39
	v_rcp_f32_e32 v58, v39
	v_mul_f32_e32 v39, 0xbfb8aa3b, v23
	v_exp_f32_e32 v39, v39
	v_lshlrev_b32_e32 v64, 16, v109
	v_and_b32_e32 v65, 0xffff0000, v109
	v_and_b32_e32 v21, 0xffff0000, v108
	v_add_f32_e32 v39, 1.0, v39
	v_rcp_f32_e32 v59, v39
	s_nop 0
	v_pk_mul_f32 v[22:23], v[58:59], v[22:23]
	v_lshlrev_b32_e32 v58, 16, v101
	v_and_b32_e32 v59, 0xffff0000, v101
	v_mul_f32_e32 v17, 0xbfb8aa3b, v64
	v_exp_f32_e32 v17, v17
	v_pk_add_f32 v[58:59], v[58:59], v[60:61]
	v_add_f32_e32 v17, 1.0, v17
	v_rcp_f32_e32 v60, v17
	v_mul_f32_e32 v17, 0xbfb8aa3b, v65
	v_exp_f32_e32 v17, v17
	s_nop 0
	v_add_f32_e32 v17, 1.0, v17
	v_rcp_f32_e32 v61, v17
	v_and_b32_e32 v17, 0xffff0000, v104
	v_pk_mul_f32 v[60:61], v[60:61], v[64:65]
	v_lshlrev_b32_e32 v64, 16, v100
	v_and_b32_e32 v65, 0xffff0000, v100
	v_lshlrev_b32_e32 v16, 16, v104
	v_lshlrev_b32_e32 v20, 16, v108
	v_mul_f32_e32 v55, 0xbfb8aa3b, v20
	v_exp_f32_e32 v55, v55
	v_pk_add_f32 v[16:17], v[64:65], v[16:17]
	v_add_f32_e32 v55, 1.0, v55
	v_add_f32_e32 v39, 0, v16
	v_add_f32_e32 v39, v17, v39
	v_rcp_f32_e32 v56, v55
	v_mul_f32_e32 v55, 0xbfb8aa3b, v21
	v_add_f32_e32 v39, v58, v39
	v_exp_f32_e32 v55, v55
	v_add_f32_e32 v39, v59, v39
	v_add_f32_e32 v39, v18, v39
	v_add_f32_e32 v39, v19, v39
	v_add_f32_e32 v39, v44, v39
	v_add_f32_e32 v55, 1.0, v55
	v_add_f32_e32 v39, v45, v39
	v_rcp_f32_e32 v57, v55
	ds_bpermute_b32 v55, v49, v39
	v_pk_mul_f32 v[20:21], v[56:57], v[20:21]
	s_waitcnt lgkmcnt(0)
	v_add_f32_e32 v39, v39, v55
	ds_bpermute_b32 v55, v50, v39
	s_waitcnt lgkmcnt(0)
	v_add_f32_e32 v39, v39, v55
	ds_bpermute_b32 v55, v51, v39
	s_waitcnt lgkmcnt(0)
	v_add_f32_e32 v39, v39, v55
	v_mul_f32_e32 v56, 0x3c800000, v39
	v_pk_add_f32 v[16:17], v[16:17], v[56:57] op_sel_hi:[1,0] neg_lo:[0,1] neg_hi:[0,1]
	v_pk_add_f32 v[58:59], v[58:59], v[56:57] op_sel_hi:[1,0] neg_lo:[0,1] neg_hi:[0,1]
	v_pk_mul_f32 v[64:65], v[16:17], v[16:17]
	v_pk_mul_f32 v[66:67], v[58:59], v[58:59]
	v_add_f32_e32 v39, v64, v65
	v_pk_add_f32 v[18:19], v[18:19], v[56:57] op_sel_hi:[1,0] neg_lo:[0,1] neg_hi:[0,1]
	v_add_f32_e32 v39, v66, v39
	v_pk_mul_f32 v[68:69], v[18:19], v[18:19]
	v_add_f32_e32 v39, v67, v39
	v_pk_add_f32 v[44:45], v[44:45], v[56:57] op_sel_hi:[1,0] neg_lo:[0,1] neg_hi:[0,1]
	v_add_f32_e32 v39, v68, v39
	v_pk_mul_f32 v[56:57], v[44:45], v[44:45]
	v_add_f32_e32 v39, v69, v39
	v_add_f32_e32 v39, v56, v39
	v_add_f32_e32 v39, v57, v39
	ds_bpermute_b32 v55, v49, v39
	s_waitcnt lgkmcnt(0)
	v_add_f32_e32 v39, v39, v55
	ds_bpermute_b32 v55, v50, v39
	s_waitcnt lgkmcnt(0)
	v_add_f32_e32 v39, v39, v55
	ds_bpermute_b32 v55, v51, v39
	s_waitcnt lgkmcnt(0)
; __device__ __forceinline__ unsigned pk2(float lo, float hi) { const f32v2_t f = {lo, hi}; const bf16v2_t b = __builtin_convertvector(f, bf16v2_t); return __builtin_bit_cast(unsigned, b); }
; __device__ __forceinline__ float siluf(float v) { return v * __builtin_amdgcn_rcpf(1.f + __expf(-v)); }
; __device__ NOINL void combine_phase(const LAS Params* lp, int l, LAS unsigned char* lds) {
;     ...
;         for (int i = 0; i < 4; ++i) {
;             const size_t row = (size_t)(row0 + 8 * w + 2 * i + (lane >> 5)); const int l32 = lane & 31;
;             float of[8], ob[8], gg[8];
;             unpack8(*(const u32x4*)(p.hbuf + row * DM + 768 + l32 * 8), of); unpack8(*(const u32x4*)(p.hyproj + row * 768 + 512 + l32 * 8), ob); unpack8(*(const u32x4*)(p.proj + row * 3072 + 2816 + l32 * 8), gg);
;             float s1 = 0.f;
; #pragma unroll
;             for (int e = 0; e < 8; ++e) { of[e] += ob[e]; s1 += of[e]; }
;             s1 += __shfl_xor(s1, 1); s1 += __shfl_xor(s1, 2); s1 += __shfl_xor(s1, 4);
;             const float mu = s1 * (1.f / 64.f); float s2 = 0.f;
; #pragma unroll
;             for (int e = 0; e < 8; ++e) { of[e] -= mu; s2 += of[e] * of[e]; }
;             s2 += __shfl_xor(s2, 1); s2 += __shfl_xor(s2, 2); s2 += __shfl_xor(s2, 4);
;             const float inv = rsqrtf(s2 * (1.f / 64.f) + 1e-6f);
;             float o[8];
; #pragma unroll
;             for (int e = 0; e < 8; ++e) o[e] = of[e] * inv * siluf(gg[e]);
;             u32x4 pk; pk.x = pk2(o[0], o[1]); pk.y = pk2(o[2], o[3]); pk.z = pk2(o[4], o[5]); pk.w = pk2(o[6], o[7]);
;             *(u32x4*)(p.hbuf + row * DM + 768 + l32 * 8) = pk;
	v_add_f32_e32 v39, v39, v55
	v_fmamk_f32 v39, v39, 0x3c800000, v211
	v_cmp_gt_f32_e32 vcc, s79, v39
	v_mul_f32_e32 v55, 0x4b800000, v39
	s_nop 0
	v_cndmask_b32_e32 v39, v39, v55, vcc
	v_rsq_f32_e32 v39, v39
	s_nop 0
	v_mul_f32_e32 v55, 0x45800000, v39
	v_cndmask_b32_e32 v56, v39, v55, vcc
	v_pk_mul_f32 v[18:19], v[18:19], v[56:57] op_sel_hi:[1,0]
	v_pk_mul_f32 v[16:17], v[16:17], v[56:57] op_sel_hi:[1,0]
	v_pk_mul_f32 v[18:19], v[22:23], v[18:19]
	v_mul_f32_e32 v22, 0xbfb8aa3b, v62
	v_mul_f32_e32 v23, 0xbfb8aa3b, v63
	v_exp_f32_e32 v22, v22
	v_exp_f32_e32 v23, v23
	v_pk_mul_f32 v[16:17], v[20:21], v[16:17]
	v_pk_mul_f32 v[20:21], v[58:59], v[56:57] op_sel_hi:[1,0]
	v_add_f32_e32 v22, 1.0, v22
	v_add_f32_e32 v23, 1.0, v23
	v_rcp_f32_e32 v22, v22
	v_rcp_f32_e32 v23, v23
	v_pk_mul_f32 v[44:45], v[44:45], v[56:57] op_sel_hi:[1,0]
	v_pk_mul_f32 v[20:21], v[60:61], v[20:21]
	v_cvt_pk_bf16_f32 v16, v16, v17
	v_pk_mul_f32 v[22:23], v[22:23], v[62:63]
	v_cvt_pk_bf16_f32 v17, v20, v21
	v_pk_mul_f32 v[22:23], v[22:23], v[44:45]
	v_cvt_pk_bf16_f32 v18, v18, v19
	v_cvt_pk_bf16_f32 v19, v22, v23
	global_store_dwordx4 v[98:99], v[16:19], off offset:1536
	s_nop 0
	s_nop 0
	s_waitcnt vmcnt(10)
	v_lshlrev_b32_e32 v60, 16, v121
	v_lshlrev_b32_e32 v44, 16, v117
	v_and_b32_e32 v45, 0xffff0000, v117
	v_and_b32_e32 v61, 0xffff0000, v121
	v_pk_add_f32 v[44:45], v[44:45], v[60:61]
	v_lshlrev_b32_e32 v60, 16, v116
	v_and_b32_e32 v61, 0xffff0000, v116
	v_lshlrev_b32_e32 v18, 16, v120
	v_and_b32_e32 v19, 0xffff0000, v120
	v_pk_add_f32 v[18:19], v[60:61], v[18:19]
	v_lshlrev_b32_e32 v60, 16, v119
	v_and_b32_e32 v61, 0xffff0000, v119
	s_waitcnt vmcnt(9)
	v_lshlrev_b32_e32 v22, 16, v124
	v_mul_f32_e32 v39, 0xbfb8aa3b, v22
	v_exp_f32_e32 v39, v39
	v_and_b32_e32 v23, 0xffff0000, v124
	v_lshlrev_b32_e32 v62, 16, v125
	v_and_b32_e32 v63, 0xffff0000, v125
	v_add_f32_e32 v39, 1.0, v39
	v_rcp_f32_e32 v58, v39
	v_mul_f32_e32 v39, 0xbfb8aa3b, v23
	v_exp_f32_e32 v39, v39
	v_lshlrev_b32_e32 v64, 16, v123
	v_and_b32_e32 v65, 0xffff0000, v123
	v_and_b32_e32 v21, 0xffff0000, v122
	v_add_f32_e32 v39, 1.0, v39
	v_rcp_f32_e32 v59, v39
	s_nop 0
	v_pk_mul_f32 v[22:23], v[58:59], v[22:23]
	v_lshlrev_b32_e32 v58, 16, v115
	v_and_b32_e32 v59, 0xffff0000, v115
	v_mul_f32_e32 v17, 0xbfb8aa3b, v64
	v_exp_f32_e32 v17, v17
	v_pk_add_f32 v[58:59], v[58:59], v[60:61]
	v_add_f32_e32 v17, 1.0, v17
	v_rcp_f32_e32 v60, v17
	v_mul_f32_e32 v17, 0xbfb8aa3b, v65
	v_exp_f32_e32 v17, v17
	s_nop 0
	v_add_f32_e32 v17, 1.0, v17
	v_rcp_f32_e32 v61, v17
	v_and_b32_e32 v17, 0xffff0000, v118
	v_pk_mul_f32 v[60:61], v[60:61], v[64:65]
	v_lshlrev_b32_e32 v64, 16, v114
	v_and_b32_e32 v65, 0xffff0000, v114
	v_lshlrev_b32_e32 v16, 16, v118
	v_lshlrev_b32_e32 v20, 16, v122
	v_mul_f32_e32 v55, 0xbfb8aa3b, v20
	v_exp_f32_e32 v55, v55
	v_pk_add_f32 v[16:17], v[64:65], v[16:17]
	v_add_f32_e32 v55, 1.0, v55
	v_add_f32_e32 v39, 0, v16
	v_add_f32_e32 v39, v17, v39
	v_rcp_f32_e32 v56, v55
	v_mul_f32_e32 v55, 0xbfb8aa3b, v21
	v_add_f32_e32 v39, v58, v39
	v_exp_f32_e32 v55, v55
	v_add_f32_e32 v39, v59, v39
	v_add_f32_e32 v39, v18, v39
	v_add_f32_e32 v39, v19, v39
	v_add_f32_e32 v39, v44, v39
	v_add_f32_e32 v55, 1.0, v55
	v_add_f32_e32 v39, v45, v39
	v_rcp_f32_e32 v57, v55
	ds_bpermute_b32 v55, v49, v39
	v_pk_mul_f32 v[20:21], v[56:57], v[20:21]
	s_waitcnt lgkmcnt(0)
	v_add_f32_e32 v39, v39, v55
	ds_bpermute_b32 v55, v50, v39
	s_waitcnt lgkmcnt(0)
	v_add_f32_e32 v39, v39, v55
	ds_bpermute_b32 v55, v51, v39
	s_waitcnt lgkmcnt(0)
	v_add_f32_e32 v39, v39, v55
	v_mul_f32_e32 v56, 0x3c800000, v39
	v_pk_add_f32 v[16:17], v[16:17], v[56:57] op_sel_hi:[1,0] neg_lo:[0,1] neg_hi:[0,1]
	v_pk_add_f32 v[58:59], v[58:59], v[56:57] op_sel_hi:[1,0] neg_lo:[0,1] neg_hi:[0,1]
	v_pk_mul_f32 v[64:65], v[16:17], v[16:17]
	v_pk_mul_f32 v[66:67], v[58:59], v[58:59]
	v_add_f32_e32 v39, v64, v65
	v_pk_add_f32 v[18:19], v[18:19], v[56:57] op_sel_hi:[1,0] neg_lo:[0,1] neg_hi:[0,1]
	v_add_f32_e32 v39, v66, v39
	v_pk_mul_f32 v[68:69], v[18:19], v[18:19]
	v_add_f32_e32 v39, v67, v39
	v_pk_add_f32 v[44:45], v[44:45], v[56:57] op_sel_hi:[1,0] neg_lo:[0,1] neg_hi:[0,1]
	v_add_f32_e32 v39, v68, v39
	v_pk_mul_f32 v[56:57], v[44:45], v[44:45]
	v_add_f32_e32 v39, v69, v39
	v_add_f32_e32 v39, v56, v39
	v_add_f32_e32 v39, v57, v39
	ds_bpermute_b32 v55, v49, v39
	s_waitcnt lgkmcnt(0)
	v_add_f32_e32 v39, v39, v55
	ds_bpermute_b32 v55, v50, v39
	s_waitcnt lgkmcnt(0)
	v_add_f32_e32 v39, v39, v55
	ds_bpermute_b32 v55, v51, v39
	s_waitcnt lgkmcnt(0)
; __device__ __forceinline__ unsigned pk2(float lo, float hi) { const f32v2_t f = {lo, hi}; const bf16v2_t b = __builtin_convertvector(f, bf16v2_t); return __builtin_bit_cast(unsigned, b); }
; __device__ __forceinline__ float siluf(float v) { return v * __builtin_amdgcn_rcpf(1.f + __expf(-v)); }
; __device__ NOINL void combine_phase(const LAS Params* lp, int l, LAS unsigned char* lds) {
;     ...
;     for (int tt = blockIdx.x; tt < ntt; tt += gridDim.x) {
;     ...
;         for (int i = 0; i < 4; ++i) {
;             const size_t row = (size_t)(row0 + 8 * w + 2 * i + (lane >> 5)); const int l32 = lane & 31;
;             float of[8], ob[8], gg[8];
;             unpack8(*(const u32x4*)(p.hbuf + row * DM + 768 + l32 * 8), of); unpack8(*(const u32x4*)(p.hyproj + row * 768 + 512 + l32 * 8), ob); unpack8(*(const u32x4*)(p.proj + row * 3072 + 2816 + l32 * 8), gg);
;             float s1 = 0.f;
; #pragma unroll
;             for (int e = 0; e < 8; ++e) { of[e] += ob[e]; s1 += of[e]; }
;             s1 += __shfl_xor(s1, 1); s1 += __shfl_xor(s1, 2); s1 += __shfl_xor(s1, 4);
;             const float mu = s1 * (1.f / 64.f); float s2 = 0.f;
; #pragma unroll
;             for (int e = 0; e < 8; ++e) { of[e] -= mu; s2 += of[e] * of[e]; }
;             s2 += __shfl_xor(s2, 1); s2 += __shfl_xor(s2, 2); s2 += __shfl_xor(s2, 4);
;             const float inv = rsqrtf(s2 * (1.f / 64.f) + 1e-6f);
;             float o[8];
; #pragma unroll
;             for (int e = 0; e < 8; ++e) o[e] = of[e] * inv * siluf(gg[e]);
;             u32x4 pk; pk.x = pk2(o[0], o[1]); pk.y = pk2(o[2], o[3]); pk.z = pk2(o[4], o[5]); pk.w = pk2(o[6], o[7]);
;             *(u32x4*)(p.hbuf + row * DM + 768 + l32 * 8) = pk;
	v_add_f32_e32 v39, v39, v55
	v_fmamk_f32 v39, v39, 0x3c800000, v211
	v_cmp_gt_f32_e32 vcc, s79, v39
	v_mul_f32_e32 v55, 0x4b800000, v39
	s_nop 0
	v_cndmask_b32_e32 v39, v39, v55, vcc
	v_rsq_f32_e32 v39, v39
	s_nop 0
	v_mul_f32_e32 v55, 0x45800000, v39
	v_cndmask_b32_e32 v56, v39, v55, vcc
	v_pk_mul_f32 v[18:19], v[18:19], v[56:57] op_sel_hi:[1,0]
	v_pk_mul_f32 v[16:17], v[16:17], v[56:57] op_sel_hi:[1,0]
	v_pk_mul_f32 v[18:19], v[22:23], v[18:19]
	v_mul_f32_e32 v22, 0xbfb8aa3b, v62
	v_mul_f32_e32 v23, 0xbfb8aa3b, v63
	v_exp_f32_e32 v22, v22
	v_exp_f32_e32 v23, v23
	v_pk_mul_f32 v[16:17], v[20:21], v[16:17]
	v_pk_mul_f32 v[20:21], v[58:59], v[56:57] op_sel_hi:[1,0]
	v_add_f32_e32 v22, 1.0, v22
	v_add_f32_e32 v23, 1.0, v23
	v_rcp_f32_e32 v22, v22
	v_rcp_f32_e32 v23, v23
	v_pk_mul_f32 v[44:45], v[44:45], v[56:57] op_sel_hi:[1,0]
	v_pk_mul_f32 v[20:21], v[60:61], v[20:21]
	v_cvt_pk_bf16_f32 v16, v16, v17
	v_pk_mul_f32 v[22:23], v[22:23], v[62:63]
	v_cvt_pk_bf16_f32 v17, v20, v21
	v_pk_mul_f32 v[22:23], v[22:23], v[44:45]
	v_cvt_pk_bf16_f32 v18, v18, v19
	v_cvt_pk_bf16_f32 v19, v22, v23
	global_store_dwordx4 v[112:113], v[16:19], off offset:1536
	s_nop 0
	v_readlane_b32 s0, v254, 33
	s_add_i32 s27, s27, s0
	s_cmp_lt_i32 s29, s6
	s_waitcnt vmcnt(9)
	v_lshlrev_b32_e32 v44, 16, v129
	v_and_b32_e32 v45, 0xffff0000, v129
	s_waitcnt vmcnt(8)
	v_lshlrev_b32_e32 v56, 16, v81
	v_and_b32_e32 v57, 0xffff0000, v81
	v_pk_add_f32 v[44:45], v[44:45], v[56:57]
	v_lshlrev_b32_e32 v56, 16, v128
	v_and_b32_e32 v57, 0xffff0000, v128
	v_lshlrev_b32_e32 v18, 16, v80
	v_and_b32_e32 v19, 0xffff0000, v80
	s_waitcnt vmcnt(7)
	v_lshlrev_b32_e32 v22, 16, v132
	v_mul_f32_e32 v37, 0xbfb8aa3b, v22
	v_exp_f32_e32 v37, v37
	v_and_b32_e32 v23, 0xffff0000, v132
	v_lshlrev_b32_e32 v58, 16, v133
	v_and_b32_e32 v59, 0xffff0000, v133
	v_add_f32_e32 v37, 1.0, v37
	v_rcp_f32_e32 v42, v37
	v_mul_f32_e32 v37, 0xbfb8aa3b, v23
	v_exp_f32_e32 v37, v37
	v_lshlrev_b32_e32 v60, 16, v131
	v_pk_add_f32 v[18:19], v[56:57], v[18:19]
	v_lshlrev_b32_e32 v56, 16, v79
	v_add_f32_e32 v37, 1.0, v37
	v_rcp_f32_e32 v43, v37
	v_and_b32_e32 v57, 0xffff0000, v79
	v_and_b32_e32 v61, 0xffff0000, v131
	v_and_b32_e32 v21, 0xffff0000, v130
	v_pk_mul_f32 v[22:23], v[42:43], v[22:23]
	v_lshlrev_b32_e32 v42, 16, v127
	v_and_b32_e32 v43, 0xffff0000, v127
	v_mul_f32_e32 v17, 0xbfb8aa3b, v60
	v_exp_f32_e32 v17, v17
	v_pk_add_f32 v[42:43], v[42:43], v[56:57]
	v_mul_f32_e32 v41, 0xbfb8aa3b, v21
	v_exp_f32_e32 v41, v41
	v_add_f32_e32 v17, 1.0, v17
	v_rcp_f32_e32 v56, v17
	v_mul_f32_e32 v17, 0xbfb8aa3b, v61
	v_exp_f32_e32 v17, v17
	v_add_f32_e32 v41, 1.0, v41
	v_rcp_f32_e32 v41, v41
	v_add_f32_e32 v17, 1.0, v17
	v_rcp_f32_e32 v57, v17
	v_and_b32_e32 v17, 0xffff0000, v78
	v_pk_mul_f32 v[56:57], v[56:57], v[60:61]
	v_lshlrev_b32_e32 v60, 16, v126
	v_and_b32_e32 v61, 0xffff0000, v126
	v_lshlrev_b32_e32 v16, 16, v78
	v_lshlrev_b32_e32 v20, 16, v130
	v_mul_f32_e32 v40, 0xbfb8aa3b, v20
	v_pk_add_f32 v[16:17], v[60:61], v[16:17]
	v_exp_f32_e32 v40, v40
	v_add_f32_e32 v37, 0, v16
	v_add_f32_e32 v37, v17, v37
	v_add_f32_e32 v37, v42, v37
	v_add_f32_e32 v40, 1.0, v40
	v_add_f32_e32 v37, v43, v37
	v_rcp_f32_e32 v40, v40
	v_add_f32_e32 v37, v18, v37
	v_add_f32_e32 v37, v19, v37
	v_add_f32_e32 v37, v44, v37
	v_add_f32_e32 v37, v45, v37
	v_pk_mul_f32 v[20:21], v[40:41], v[20:21]
	ds_bpermute_b32 v40, v49, v37
	s_waitcnt lgkmcnt(0)
	v_add_f32_e32 v37, v37, v40
	ds_bpermute_b32 v40, v50, v37
	s_waitcnt lgkmcnt(0)
	v_add_f32_e32 v37, v37, v40
	ds_bpermute_b32 v40, v51, v37
	s_waitcnt lgkmcnt(0)
	v_add_f32_e32 v37, v37, v40
	v_mul_f32_e32 v40, 0x3c800000, v37
	v_pk_add_f32 v[16:17], v[16:17], v[40:41] op_sel_hi:[1,0] neg_lo:[0,1] neg_hi:[0,1]
	v_pk_add_f32 v[42:43], v[42:43], v[40:41] op_sel_hi:[1,0] neg_lo:[0,1] neg_hi:[0,1]
	v_pk_mul_f32 v[60:61], v[16:17], v[16:17]
	v_pk_mul_f32 v[62:63], v[42:43], v[42:43]
	v_add_f32_e32 v37, v60, v61
	v_pk_add_f32 v[18:19], v[18:19], v[40:41] op_sel_hi:[1,0] neg_lo:[0,1] neg_hi:[0,1]
	v_add_f32_e32 v37, v62, v37
	v_pk_mul_f32 v[64:65], v[18:19], v[18:19]
	v_add_f32_e32 v37, v63, v37
	v_pk_add_f32 v[40:41], v[44:45], v[40:41] op_sel_hi:[1,0] neg_lo:[0,1] neg_hi:[0,1]
	v_add_f32_e32 v37, v64, v37
	v_pk_mul_f32 v[44:45], v[40:41], v[40:41]
	v_add_f32_e32 v37, v65, v37
	v_add_f32_e32 v37, v44, v37
	v_add_f32_e32 v37, v45, v37
	ds_bpermute_b32 v44, v49, v37
	s_waitcnt lgkmcnt(0)
	v_add_f32_e32 v37, v37, v44
	ds_bpermute_b32 v44, v50, v37
	s_waitcnt lgkmcnt(0)
	v_add_f32_e32 v37, v37, v44
	ds_bpermute_b32 v44, v51, v37
	s_waitcnt lgkmcnt(0)
	v_add_f32_e32 v37, v37, v44
	v_fmamk_f32 v37, v37, 0x3c800000, v211
	v_cmp_gt_f32_e32 vcc, s79, v37
	v_mul_f32_e32 v44, 0x4b800000, v37
	s_nop 0
	v_cndmask_b32_e32 v37, v37, v44, vcc
	v_rsq_f32_e32 v37, v37
	s_nop 0
	v_mul_f32_e32 v44, 0x45800000, v37
	v_cndmask_b32_e32 v44, v37, v44, vcc
	v_pk_mul_f32 v[18:19], v[18:19], v[44:45] op_sel_hi:[1,0]
	v_pk_mul_f32 v[16:17], v[16:17], v[44:45] op_sel_hi:[1,0]
	v_pk_mul_f32 v[18:19], v[22:23], v[18:19]
	v_mul_f32_e32 v22, 0xbfb8aa3b, v58
	v_mul_f32_e32 v23, 0xbfb8aa3b, v59
	v_exp_f32_e32 v22, v22
	v_exp_f32_e32 v23, v23
	v_pk_mul_f32 v[16:17], v[20:21], v[16:17]
	v_pk_mul_f32 v[20:21], v[42:43], v[44:45] op_sel_hi:[1,0]
	v_add_f32_e32 v22, 1.0, v22
	v_add_f32_e32 v23, 1.0, v23
	v_rcp_f32_e32 v22, v22
	v_rcp_f32_e32 v23, v23
	v_pk_mul_f32 v[40:41], v[40:41], v[44:45] op_sel_hi:[1,0]
	v_pk_mul_f32 v[20:21], v[56:57], v[20:21]
	v_cvt_pk_bf16_f32 v16, v16, v17
	v_pk_mul_f32 v[22:23], v[22:23], v[58:59]
	v_cvt_pk_bf16_f32 v17, v20, v21
	v_pk_mul_f32 v[22:23], v[22:23], v[40:41]
	v_cvt_pk_bf16_f32 v18, v18, v19
	v_cvt_pk_bf16_f32 v19, v22, v23
	global_store_dwordx4 v[70:71], v[16:19], off offset:1536
	s_cbranch_scc0 .LBB0_1405
